# memory-attention item prologue: both K/V tile loads issued together with a counted vmcnt ladder (was load-wait-store twice)
# baseline (speedup 1.0000x reference)
; DI int my_tid() { int t = threadIdx.x; asm volatile("" : "+v"(t)); return t; }
; template <int DK>
; DI void attn_core(const bf16x8 (&qf)[DK / 16], const short* Kg, const short* VTg, size_t ldvt, int ntiles, char* smem,
;                   f32x16 (&O)[2], float& lsum) {
;     ...
;   const int kfo = pr * KROW + h * 16;
;   const int vfo = KT_BYTES + r * VROW + h * 16;
;   AGLOAD(0);
;   ASTORE(0);
;   AGLOAD(ntiles > 1 ? 1 : 0);
;   ASTORE(1);
;   __syncthreads();
; DI void memattn_item(PRef p, int layer, int mt, int head, char* smem) {
;   const int tid = my_tid(), lane = tid & 63, w = tid >> 6, r = lane & 31, h = lane >> 5;
;   const int tok = mt * 256 + w * 32 + r;
;   const int seq = tok_seq(mt * 256);
;   const short* Q = (const short*)(p.ws + OFF_QMEM);
;   bf16x8 qf[4];
; #pragma unroll
;   for (int ks = 0; ks < 4; ks++) qf[ks] = *(const bf16x8*)(Q + (size_t)tok * 256 + head * 64 + ks * 16 + 8 * h);
;   const size_t hb = ((size_t)(layer * NSEQ + seq) * 4 + head) * 256 * 64;
;   f32x16 O[2];
;   float lsum;
;   attn_core<64>(qf, (const short*)(p.ws + OFF_KMEM) + hb, (const short*)(p.ws + OFF_VMEM) + hb, 256, 2, smem, O, lsum);
.LBB0_142:
	s_cmpk_gt_i32 s39, 0x9ff
	s_mov_b64 s[42:43], -1
	s_cbranch_scc0 .LBB0_144
	s_waitcnt vmcnt(0)
	v_mov_b32_e32 v2, v196
	s_add_i32 s28, s38, 0x4000
	v_ashrrev_i32_e32 v0, 1, v2
	s_and_b32 s28, s28, 0x7fffff00
	v_and_b32_e32 v0, 0xffffffe0, v0
	v_add_u32_e32 v0, s28, v0
	v_and_or_b32 v80, v2, 31, v0
	v_ashrrev_i32_e32 v81, 31, v80
	s_and_b32 s42, s39, 3
	v_lshlrev_b64 v[0:1], 9, v[80:81]
	v_lshl_add_u64 v[0:1], s[6:7], 0, v[0:1]
	s_lshl_b32 s30, s42, 7
	v_lshrrev_b32_e32 v2, 1, v2
	v_lshl_add_u64 v[0:1], v[0:1], 0, s[30:31]
	s_waitcnt vmcnt(7)
	v_and_b32_e32 v128, 16, v2
	v_lshl_add_u64 v[0:1], v[0:1], 0, v[128:129]
	s_lshr_b32 s28, s38, 12
	v_mov_b32_e32 v2, v196
	s_add_i32 s16, s39, 0xfffff600
	global_load_dwordx4 v[60:63], v[0:1], off
	global_load_dwordx4 v[56:59], v[0:1], off offset:32
	global_load_dwordx4 v[52:55], v[0:1], off offset:64
	global_load_dwordx4 v[48:51], v[0:1], off offset:96
	s_add_i32 s28, s28, 1
	s_cmpk_gt_u32 s16, 0xff
	v_lshlrev_b32_e32 v0, 1, v2
	v_and_b32_e32 v10, 8, v0
	v_ashrrev_i32_e32 v0, 31, v2
	s_cselect_b32 s16, s28, 0
	v_readlane_b32 s28, v226, 46
	v_lshrrev_b32_e32 v0, 29, v0
	v_readlane_b32 s29, v226, 47
	s_mul_i32 s28, s28, 17
	v_add_u32_e32 v0, v2, v0
	s_add_i32 s28, s16, s28
	s_mov_b32 s29, s31
	v_lshrrev_b32_e32 v0, 3, v0
	s_lshl_b64 s[28:29], s[28:29], 17
	s_lshl_b32 s16, s42, 15
	v_add_lshl_u32 v81, v0, v2, 4
	v_add_u32_e32 v0, 0x200, v2
	s_or_b32 s16, s28, s16
	v_ashrrev_i32_e32 v1, 31, v0
	v_lshlrev_b32_e32 v4, 4, v2
	s_add_u32 s42, s10, s16
	v_lshrrev_b32_e32 v1, 29, v1
	v_and_b32_e32 v128, 0xf0, v4
	v_lshlrev_b32_e32 v4, 3, v2
	s_addc_u32 s43, s11, s29
	v_add_u32_e32 v1, v0, v1
	v_ashrrev_i32_e32 v16, 4, v2
	v_ashrrev_i32_e32 v5, 31, v4
	s_add_u32 s28, s12, s16
	v_lshrrev_b32_e32 v1, 3, v1
	v_ashrrev_i32_e32 v17, 31, v16
	v_lshlrev_b64 v[18:19], 1, v[4:5]
	v_add_u32_e32 v4, 0x1000, v4
	s_addc_u32 s29, s13, s29
	v_add_lshl_u32 v92, v1, v0, 4
	v_lshlrev_b64 v[0:1], 9, v[16:17]
	v_ashrrev_i32_e32 v5, 31, v4
	v_lshrrev_b32_e32 v3, 1, v2
	v_lshl_add_u64 v[8:9], s[28:29], 0, v[0:1]
	v_lshl_add_u64 v[0:1], s[42:43], 0, v[18:19]
	v_lshlrev_b64 v[20:21], 1, v[4:5]
	v_and_b32_e32 v32, 31, v2
	v_and_b32_e32 v11, 4, v3
	v_and_b32_e32 v12, 19, v2
	v_and_b32_e32 v33, 16, v3
	global_load_dwordx4 v[0:3], v[0:1], off
	v_lshl_add_u64 v[4:5], s[42:43], 0, v[20:21]
	v_lshl_add_u64 v[84:85], v[8:9], 0, v[128:129]
	global_load_dwordx4 v[4:7], v[4:5], off
	v_or3_b32 v10, v12, v10, v11
	s_movk_i32 s16, 0x90
	v_add_co_u32_e32 v86, vcc, s84, v84
	v_mad_u32_u24 v93, v10, s16, v33
	global_load_dwordx4 v[8:11], v[84:85], off
	v_addc_co_u32_e32 v87, vcc, 0, v85, vcc
	global_load_dwordx4 v[12:15], v[86:87], off
	s_movk_i32 s16, 0x110
	v_mad_u64_u32 v[82:83], s[28:29], v16, s16, v[128:129]
	s_add_u32 s28, s42, 0x4000
	s_addc_u32 s29, s43, 0
	v_lshl_add_u64 v[88:89], s[28:29], 0, v[18:19]
	v_lshl_add_u64 v[90:91], s[28:29], 0, v[20:21]
	v_add_u32_e32 v94, 0x11800, v82
	global_load_dwordx4 v[64:67], v[88:89], off
	global_load_dwordx4 v[68:71], v[90:91], off
	global_load_dwordx4 v[72:75], v[84:85], off offset:256
	global_load_dwordx4 v[76:79], v[86:87], off offset:256
	s_waitcnt vmcnt(7)
	ds_write_b128 v81, v[0:3]
	s_waitcnt vmcnt(6)
	ds_write_b128 v92, v[4:7]
	s_waitcnt vmcnt(5)
	ds_write_b128 v82, v[8:11] offset:18432
	s_waitcnt vmcnt(4)
	ds_write_b128 v82, v[12:15] offset:27136
	s_waitcnt vmcnt(3)
	ds_write_b128 v81, v[64:67] offset:35840
	s_waitcnt vmcnt(2)
	ds_write_b128 v92, v[68:71] offset:35840
	s_waitcnt vmcnt(1)
	ds_write_b128 v82, v[72:75] offset:54272
	s_waitcnt vmcnt(0)
	ds_write_b128 v82, v[76:79] offset:62976
	s_waitcnt lgkmcnt(0)
	s_barrier
	ds_read_b128 v[0:3], v93
	ds_read_b128 v[16:19], v93 offset:32
	ds_read_b128 v[20:23], v93 offset:64
	ds_read_b128 v[24:27], v93 offset:96
	global_load_dwordx4 v[64:67], v[88:89], off
	global_load_dwordx4 v[72:75], v[90:91], off
	global_load_dwordx4 v[68:71], v[84:85], off offset:256
	global_load_dwordx4 v[76:79], v[86:87], off offset:256
	s_waitcnt lgkmcnt(3)
	v_mfma_f32_32x32x16_bf16 v[0:15], v[0:3], v[60:63], 0
	s_waitcnt lgkmcnt(2)
	v_mfma_f32_32x32x16_bf16 v[0:15], v[16:19], v[56:59], v[0:15]
	s_waitcnt lgkmcnt(1)
	v_mfma_f32_32x32x16_bf16 v[0:15], v[20:23], v[52:55], v[0:15]
	s_waitcnt lgkmcnt(0)
	v_mfma_f32_32x32x16_bf16 v[0:15], v[24:27], v[48:51], v[0:15]
	ds_read_b128 v[16:19], v93 offset:4608
	ds_read_b128 v[20:23], v93 offset:4640
	ds_read_b128 v[24:27], v93 offset:4672
	ds_read_b128 v[28:31], v93 offset:4704
	s_nop 7
	v_exp_f32_e32 v0, v0
	v_exp_f32_e32 v1, v1
	v_exp_f32_e32 v2, v2
	v_exp_f32_e32 v3, v3
	v_add_f32_e32 v34, 0, v0
	v_exp_f32_e32 v4, v4
	v_add_f32_e32 v34, v1, v34
	v_exp_f32_e32 v5, v5
	v_add_f32_e32 v34, v2, v34
	v_exp_f32_e32 v6, v6
	v_add_f32_e32 v34, v3, v34
	v_exp_f32_e32 v7, v7
	v_add_f32_e32 v34, v4, v34
	v_exp_f32_e32 v8, v8
	v_add_f32_e32 v34, v5, v34
	v_exp_f32_e32 v9, v9
	v_add_f32_e32 v34, v6, v34
	v_exp_f32_e32 v10, v10
	v_add_f32_e32 v34, v7, v34
	v_exp_f32_e32 v11, v11
	v_add_f32_e32 v34, v8, v34
	v_exp_f32_e32 v12, v12
	v_add_f32_e32 v34, v9, v34
	v_exp_f32_e32 v13, v13
	v_add_f32_e32 v34, v10, v34
	v_exp_f32_e32 v14, v14
	v_add_f32_e32 v34, v11, v34
	v_exp_f32_e32 v15, v15
	v_add_f32_e32 v34, v12, v34
	v_add_f32_e32 v34, v13, v34
	v_add_f32_e32 v34, v14, v34
	v_add_f32_e32 v34, v15, v34
	v_cvt_pk_bf16_f32 v96, v0, v1
	v_cvt_pk_bf16_f32 v100, v8, v9
	v_cvt_pk_bf16_f32 v97, v2, v3
	v_cvt_pk_bf16_f32 v101, v10, v11
	v_cvt_pk_bf16_f32 v98, v4, v5
	v_cvt_pk_bf16_f32 v102, v12, v13
	v_cvt_pk_bf16_f32 v99, v6, v7
	v_cvt_pk_bf16_f32 v103, v14, v15
	s_waitcnt lgkmcnt(3)
	v_mfma_f32_32x32x16_bf16 v[0:15], v[16:19], v[60:63], 0
	s_waitcnt lgkmcnt(2)
; #define KLOAD(kf_, base)                                                                       \
;   { _Pragma("unroll") for (int ks = 0; ks < NKS; ks++) kf_[ks] = *(const bf16x8*)((base) + kfo + ks * 32); }
; #define VLOAD(vf_, base)                                                                       \
;   { _Pragma("unroll") for (int q = 0; q < 4; q++) vf_[q] = *(const bf16x8*)((base) + vfo + (q >> 1) * 32 * VROW + (q & 1) * 32); }
; #define QKM(dst, kf_)                                                                          \
;   {                                                                                            \
;     _Pragma("unroll") for (int i = 0; i < 16; i++) dst[i] = 0.f;                               \
;     _Pragma("unroll") for (int ks = 0; ks < NKS; ks++) dst = MFMA(kf_[ks], qf[ks], dst);       \
;   }
; #define SB() __builtin_amdgcn_sched_barrier(0)
; template <int DK>
; DI void attn_core(const bf16x8 (&qf)[DK / 16], const short* Kg, const short* VTg, size_t ldvt, int ntiles, char* smem,
;                   f32x16 (&O)[2], float& lsum) {
;     ...
;   for (int t = 0; t < ntiles; t++) {
;     const int tn = t + 2 < ntiles ? t + 2 : ntiles - 1;
;     AGLOAD(tn);
;     const char* cur = smem + sc * ST;
;     const char* nxt = smem + sn * ST;
;     f32x16 Sn;
;     bf16x8 pa, pb, qa, qb;
;     bf16x8 kf[NKS], vf[4];
;     KLOAD(kf, cur + 32 * KROW);
;     SB();
;     SOFTMAX(Sc, pa, pb, l0);
;     SB();
;     QKM(Sn, kf);
;     SB();
;     KLOAD(kf, cur + 64 * KROW);
;     VLOAD(vf, cur);
;     SB();
;     SOFTMAX(Sn, qa, qb, l0);
;     SB();
;     QKM(Sc, kf);
;     PVM(vf, pa, pb);
;     SB();
;     KLOAD(kf, cur + 96 * KROW);
;     VLOAD(vf, cur + 64);
;     SB();
;     SOFTMAX(Sc, pa, pb, l0);
;     SB();
;     QKM(Sn, kf);
;     PVM(vf, qa, qb);
;     SB();
;     KLOAD(kf, nxt);
;     VLOAD(vf, cur + 128);
;     SB();
;     SOFTMAX(Sn, qa, qb, l0);
;     SB();
;     QKM(Sc, kf);
;     PVM(vf, pa, pb);
;     SB();
;     VLOAD(vf, cur + 192);
;     PVM(vf, qa, qb);
;     ASTORE(sw);
;     __syncthreads();
	v_mfma_f32_32x32x16_bf16 v[0:15], v[20:23], v[56:59], v[0:15]
	s_waitcnt lgkmcnt(1)
	v_mfma_f32_32x32x16_bf16 v[0:15], v[24:27], v[52:55], v[0:15]
	s_waitcnt lgkmcnt(0)
	v_mfma_f32_32x32x16_bf16 v[0:15], v[28:31], v[48:51], v[0:15]
	v_mad_u32_u24 v83, v32, s16, v33
	ds_read_b128 v[16:19], v93 offset:9216
	ds_read_b128 v[20:23], v93 offset:9248
	ds_read_b128 v[24:27], v93 offset:9280
	ds_read_b128 v[28:31], v93 offset:9312
	ds_read_b128 v[104:107], v83 offset:18432
	ds_read_b128 v[108:111], v83 offset:18464
	ds_read_b128 v[112:115], v83 offset:27136
	ds_read_b128 v[116:119], v83 offset:27168
	s_nop 2
	v_exp_f32_e32 v0, v0
	v_exp_f32_e32 v1, v1
	v_exp_f32_e32 v2, v2
	v_exp_f32_e32 v3, v3
	v_add_f32_e32 v32, v0, v34
	v_exp_f32_e32 v4, v4
	v_add_f32_e32 v32, v1, v32
	v_exp_f32_e32 v5, v5
	v_add_f32_e32 v32, v2, v32
	v_exp_f32_e32 v6, v6
	v_add_f32_e32 v32, v3, v32
	v_exp_f32_e32 v7, v7
	v_add_f32_e32 v32, v4, v32
	v_exp_f32_e32 v8, v8
	v_add_f32_e32 v32, v5, v32
	v_exp_f32_e32 v9, v9
	v_add_f32_e32 v32, v6, v32
	v_exp_f32_e32 v10, v10
	v_add_f32_e32 v32, v7, v32
	v_exp_f32_e32 v11, v11
	v_add_f32_e32 v32, v8, v32
	v_exp_f32_e32 v12, v12
	v_add_f32_e32 v32, v9, v32
	v_exp_f32_e32 v13, v13
	v_add_f32_e32 v32, v10, v32
	v_exp_f32_e32 v14, v14
	v_add_f32_e32 v32, v11, v32
	v_exp_f32_e32 v15, v15
	v_add_f32_e32 v32, v12, v32
	v_add_f32_e32 v32, v13, v32
	v_add_f32_e32 v32, v14, v32
	v_add_f32_e32 v95, v15, v32
	v_cvt_pk_bf16_f32 v120, v0, v1
	v_cvt_pk_bf16_f32 v124, v8, v9
	v_cvt_pk_bf16_f32 v121, v2, v3
	v_cvt_pk_bf16_f32 v125, v10, v11
	v_cvt_pk_bf16_f32 v122, v4, v5
	v_cvt_pk_bf16_f32 v126, v12, v13
	v_cvt_pk_bf16_f32 v123, v6, v7
	v_cvt_pk_bf16_f32 v127, v14, v15
	s_waitcnt lgkmcnt(7)
	v_mfma_f32_32x32x16_bf16 v[32:47], v[16:19], v[60:63], 0
	s_waitcnt lgkmcnt(6)
	v_mfma_f32_32x32x16_bf16 v[32:47], v[20:23], v[56:59], v[32:47]
	s_waitcnt lgkmcnt(5)
	v_mfma_f32_32x32x16_bf16 v[32:47], v[24:27], v[52:55], v[32:47]
	s_waitcnt lgkmcnt(4)
	v_mfma_f32_32x32x16_bf16 v[32:47], v[28:31], v[48:51], v[32:47]
	s_waitcnt lgkmcnt(3)
	v_mfma_f32_32x32x16_bf16 v[16:31], v[104:107], v[96:99], 0
	s_waitcnt lgkmcnt(1)
	v_mfma_f32_32x32x16_bf16 v[0:15], v[112:115], v[96:99], 0
	v_mfma_f32_32x32x16_bf16 v[16:31], v[108:111], v[100:103], v[16:31]
	s_waitcnt lgkmcnt(0)
	v_mfma_f32_32x32x16_bf16 v[0:15], v[116:119], v[100:103], v[0:15]
	ds_read_b128 v[96:99], v93 offset:13824
	ds_read_b128 v[100:103], v93 offset:13856
	ds_read_b128 v[104:107], v93 offset:13888
	ds_read_b128 v[108:111], v93 offset:13920
	ds_read_b128 v[112:115], v83 offset:18496
	ds_read_b128 v[116:119], v83 offset:18528
	ds_read_b128 v[130:133], v83 offset:27200
	ds_read_b128 v[134:137], v83 offset:27232
	v_exp_f32_e32 v32, v32
	v_exp_f32_e32 v33, v33
	v_exp_f32_e32 v34, v34
	v_exp_f32_e32 v35, v35
	v_add_f32_e32 v95, v32, v95
	v_exp_f32_e32 v36, v36
	v_add_f32_e32 v95, v33, v95
	v_exp_f32_e32 v37, v37
	v_add_f32_e32 v95, v34, v95
	v_exp_f32_e32 v38, v38
	v_add_f32_e32 v95, v35, v95
	v_exp_f32_e32 v39, v39
	v_add_f32_e32 v95, v36, v95
	v_exp_f32_e32 v40, v40
	v_add_f32_e32 v95, v37, v95
	v_exp_f32_e32 v41, v41
	v_add_f32_e32 v95, v38, v95
	v_exp_f32_e32 v42, v42
	v_add_f32_e32 v95, v39, v95
	v_exp_f32_e32 v43, v43
	v_add_f32_e32 v95, v40, v95
	v_exp_f32_e32 v44, v44
	v_add_f32_e32 v95, v41, v95
	v_exp_f32_e32 v45, v45
	v_add_f32_e32 v95, v42, v95
	v_exp_f32_e32 v46, v46
	v_add_f32_e32 v95, v43, v95
	v_exp_f32_e32 v47, v47
	v_add_f32_e32 v95, v44, v95
	v_add_f32_e32 v95, v45, v95
	v_add_f32_e32 v95, v46, v95
	v_add_f32_e32 v95, v47, v95
	v_cvt_pk_bf16_f32 v138, v32, v33
	v_cvt_pk_bf16_f32 v142, v40, v41
	v_cvt_pk_bf16_f32 v139, v34, v35
	v_cvt_pk_bf16_f32 v143, v42, v43
	v_cvt_pk_bf16_f32 v140, v36, v37
	v_cvt_pk_bf16_f32 v144, v44, v45
	v_cvt_pk_bf16_f32 v141, v38, v39
	v_cvt_pk_bf16_f32 v145, v46, v47
	s_waitcnt lgkmcnt(3)
	v_mfma_f32_32x32x16_bf16 v[16:31], v[112:115], v[120:123], v[16:31]
	s_waitcnt lgkmcnt(1)
	v_mfma_f32_32x32x16_bf16 v[0:15], v[130:133], v[120:123], v[0:15]
	v_mfma_f32_32x32x16_bf16 v[16:31], v[116:119], v[124:127], v[16:31]
	s_waitcnt lgkmcnt(0)
	v_mfma_f32_32x32x16_bf16 v[0:15], v[134:137], v[124:127], v[0:15]
	v_mfma_f32_32x32x16_bf16 v[32:47], v[96:99], v[60:63], 0
	v_mfma_f32_32x32x16_bf16 v[32:47], v[100:103], v[56:59], v[32:47]
	v_mfma_f32_32x32x16_bf16 v[32:47], v[104:107], v[52:55], v[32:47]
	ds_read_b128 v[96:99], v93 offset:35840
	ds_read_b128 v[100:103], v93 offset:35872
	ds_read_b128 v[104:107], v93 offset:35904
	ds_read_b128 v[112:115], v93 offset:35936
	ds_read_b128 v[116:119], v83 offset:18560
	ds_read_b128 v[120:123], v83 offset:18592
	ds_read_b128 v[124:127], v83 offset:27264
	ds_read_b128 v[130:133], v83 offset:27296
	v_mfma_f32_32x32x16_bf16 v[32:47], v[108:111], v[48:51], v[32:47]
	s_nop 11
	v_exp_f32_e32 v108, v32
	v_exp_f32_e32 v109, v33
	v_exp_f32_e32 v110, v34
	v_exp_f32_e32 v111, v35
	v_exp_f32_e32 v128, v36
	v_add_f32_e32 v95, v95, v108
	v_exp_f32_e32 v134, v37
	v_add_f32_e32 v95, v109, v95
	v_exp_f32_e32 v135, v38
	v_add_f32_e32 v95, v110, v95
	v_exp_f32_e32 v136, v39
	v_add_f32_e32 v95, v111, v95
	v_exp_f32_e32 v40, v40
	v_exp_f32_e32 v41, v41
	v_add_f32_e32 v95, v128, v95
	v_add_f32_e32 v95, v134, v95
	v_exp_f32_e32 v42, v42
	v_add_f32_e32 v95, v135, v95
	v_exp_f32_e32 v43, v43
	v_add_f32_e32 v95, v136, v95
	v_exp_f32_e32 v44, v44
	v_cvt_pk_bf16_f32 v36, v40, v41
	v_add_f32_e32 v40, v40, v95
	v_exp_f32_e32 v45, v45
	v_add_f32_e32 v40, v41, v40
	v_exp_f32_e32 v46, v46
	v_add_f32_e32 v40, v42, v40
	v_exp_f32_e32 v47, v47
	v_add_f32_e32 v40, v43, v40
	v_add_f32_e32 v40, v44, v40
	v_add_f32_e32 v40, v45, v40
	v_add_f32_e32 v40, v46, v40
	v_cvt_pk_bf16_f32 v32, v108, v109
	v_cvt_pk_bf16_f32 v33, v110, v111
	v_cvt_pk_bf16_f32 v37, v42, v43
	v_cvt_pk_bf16_f32 v34, v128, v134
	v_cvt_pk_bf16_f32 v38, v44, v45
	v_cvt_pk_bf16_f32 v35, v135, v136
	v_cvt_pk_bf16_f32 v39, v46, v47
	v_add_f32_e32 v108, v47, v40
	s_waitcnt lgkmcnt(3)
	v_mfma_f32_32x32x16_bf16 v[16:31], v[116:119], v[138:141], v[16:31]
	s_waitcnt lgkmcnt(1)
	v_mfma_f32_32x32x16_bf16 v[0:15], v[124:127], v[138:141], v[0:15]
	v_mfma_f32_32x32x16_bf16 v[16:31], v[120:123], v[142:145], v[16:31]
	s_waitcnt lgkmcnt(0)
	v_mfma_f32_32x32x16_bf16 v[0:15], v[130:133], v[142:145], v[0:15]
	ds_read_b128 v[40:43], v83 offset:18624
	v_add_u32_e32 v95, 0x11800, v81
	s_waitcnt lgkmcnt(0)
	v_mfma_f32_32x32x16_bf16 v[16:31], v[40:43], v[32:35], v[16:31]
	ds_read_b128 v[40:43], v83 offset:27328
	s_waitcnt lgkmcnt(0)
	v_mfma_f32_32x32x16_bf16 v[0:15], v[40:43], v[32:35], v[0:15]
	ds_read_b128 v[32:35], v83 offset:18656
	s_waitcnt lgkmcnt(0)
	v_mfma_f32_32x32x16_bf16 v[16:31], v[32:35], v[36:39], v[16:31]
	ds_read_b128 v[32:35], v83 offset:27360
	s_waitcnt vmcnt(3)
	ds_write_b128 v95, v[64:67]
	v_add_u32_e32 v64, 0x11800, v92
	s_waitcnt vmcnt(2)
	ds_write_b128 v64, v[72:75]
	s_waitcnt vmcnt(1)
	ds_write_b128 v94, v[68:71] offset:18432
	s_waitcnt vmcnt(0)
	ds_write_b128 v94, v[76:79] offset:27136
	s_waitcnt lgkmcnt(0)
	s_barrier
; #define KLOAD(kf_, base)                                                                       \
;   { _Pragma("unroll") for (int ks = 0; ks < NKS; ks++) kf_[ks] = *(const bf16x8*)((base) + kfo + ks * 32); }
; #define VLOAD(vf_, base)                                                                       \
;   { _Pragma("unroll") for (int q = 0; q < 4; q++) vf_[q] = *(const bf16x8*)((base) + vfo + (q >> 1) * 32 * VROW + (q & 1) * 32); }
; #define QKM(dst, kf_)                                                                          \
;   {                                                                                            \
;     _Pragma("unroll") for (int i = 0; i < 16; i++) dst[i] = 0.f;                               \
;     _Pragma("unroll") for (int ks = 0; ks < NKS; ks++) dst = MFMA(kf_[ks], qf[ks], dst);       \
;   }
; #define SB() __builtin_amdgcn_sched_barrier(0)
; template <int DK>
; DI void attn_core(const bf16x8 (&qf)[DK / 16], const short* Kg, const short* VTg, size_t ldvt, int ntiles, char* smem,
;                   f32x16 (&O)[2], float& lsum) {
;     ...
;   for (int t = 0; t < ntiles; t++) {
;     const int tn = t + 2 < ntiles ? t + 2 : ntiles - 1;
;     AGLOAD(tn);
;     const char* cur = smem + sc * ST;
;     const char* nxt = smem + sn * ST;
;     f32x16 Sn;
;     bf16x8 pa, pb, qa, qb;
;     bf16x8 kf[NKS], vf[4];
;     KLOAD(kf, cur + 32 * KROW);
;     SB();
;     SOFTMAX(Sc, pa, pb, l0);
;     SB();
;     QKM(Sn, kf);
;     SB();
;     KLOAD(kf, cur + 64 * KROW);
;     VLOAD(vf, cur);
;     SB();
;     SOFTMAX(Sn, qa, qb, l0);
;     SB();
;     QKM(Sc, kf);
;     PVM(vf, pa, pb);
;     SB();
;     KLOAD(kf, cur + 96 * KROW);
;     VLOAD(vf, cur + 64);
;     SB();
;     SOFTMAX(Sc, pa, pb, l0);
;     SB();
;     QKM(Sn, kf);
;     PVM(vf, qa, qb);
;     SB();
;     KLOAD(kf, nxt);
;     VLOAD(vf, cur + 128);
;     SB();
;     SOFTMAX(Sn, qa, qb, l0);
;     SB();
;     QKM(Sc, kf);
;     PVM(vf, pa, pb);
;     SB();
;     VLOAD(vf, cur + 192);
;     PVM(vf, qa, qb);
;     ASTORE(sw);
;     __syncthreads();
	global_load_dwordx4 v[68:71], v[90:91], off
	global_load_dwordx4 v[64:67], v[84:85], off offset:256
	global_load_dwordx4 v[76:79], v[88:89], off
	global_load_dwordx4 v[72:75], v[86:87], off offset:256
	v_mfma_f32_32x32x16_bf16 v[0:15], v[32:35], v[36:39], v[0:15]
	v_mfma_f32_32x32x16_bf16 v[32:47], v[96:99], v[60:63], 0
	v_mfma_f32_32x32x16_bf16 v[32:47], v[100:103], v[56:59], v[32:47]
	ds_read_b128 v[84:87], v93 offset:40448
	ds_read_b128 v[88:91], v93 offset:40480
	ds_read_b128 v[94:97], v93 offset:40512
	ds_read_b128 v[98:101], v93 offset:40544
	v_mfma_f32_32x32x16_bf16 v[32:47], v[104:107], v[52:55], v[32:47]
	v_mfma_f32_32x32x16_bf16 v[32:47], v[112:115], v[48:51], v[32:47]
	s_nop 11
	v_exp_f32_e32 v32, v32
	v_exp_f32_e32 v33, v33
	v_exp_f32_e32 v34, v34
	v_exp_f32_e32 v35, v35
	v_add_f32_e32 v102, v108, v32
	v_exp_f32_e32 v36, v36
	v_add_f32_e32 v102, v33, v102
	v_exp_f32_e32 v37, v37
	v_add_f32_e32 v102, v34, v102
	v_exp_f32_e32 v38, v38
	v_add_f32_e32 v102, v35, v102
	v_exp_f32_e32 v39, v39
	v_add_f32_e32 v102, v36, v102
	v_exp_f32_e32 v40, v40
	v_add_f32_e32 v102, v37, v102
	v_exp_f32_e32 v41, v41
	v_add_f32_e32 v102, v38, v102
	v_exp_f32_e32 v42, v42
	v_add_f32_e32 v102, v39, v102
	v_exp_f32_e32 v43, v43
	v_add_f32_e32 v102, v40, v102
	v_exp_f32_e32 v44, v44
	v_add_f32_e32 v102, v41, v102
	v_exp_f32_e32 v45, v45
	v_add_f32_e32 v102, v42, v102
	v_exp_f32_e32 v46, v46
	v_add_f32_e32 v102, v43, v102
	v_exp_f32_e32 v47, v47
	v_add_f32_e32 v102, v44, v102
	v_add_f32_e32 v102, v45, v102
	v_add_f32_e32 v102, v46, v102
	v_add_f32_e32 v126, v47, v102
	v_cvt_pk_bf16_f32 v102, v32, v33
	v_cvt_pk_bf16_f32 v106, v40, v41
	v_cvt_pk_bf16_f32 v103, v34, v35
	v_cvt_pk_bf16_f32 v107, v42, v43
	v_cvt_pk_bf16_f32 v104, v36, v37
	v_cvt_pk_bf16_f32 v108, v44, v45
	v_cvt_pk_bf16_f32 v105, v38, v39
	v_cvt_pk_bf16_f32 v109, v46, v47
	s_waitcnt lgkmcnt(3)
	v_mfma_f32_32x32x16_bf16 v[32:47], v[84:87], v[60:63], 0
	s_waitcnt lgkmcnt(2)
	v_mfma_f32_32x32x16_bf16 v[32:47], v[88:91], v[56:59], v[32:47]
	s_waitcnt lgkmcnt(1)
	v_mfma_f32_32x32x16_bf16 v[32:47], v[94:97], v[52:55], v[32:47]
	s_waitcnt lgkmcnt(0)
	v_mfma_f32_32x32x16_bf16 v[32:47], v[98:101], v[48:51], v[32:47]
	ds_read_b128 v[84:87], v93 offset:45056
	ds_read_b128 v[88:91], v93 offset:45088
	ds_read_b128 v[94:97], v93 offset:45120
	ds_read_b128 v[98:101], v93 offset:45152
	ds_read_b128 v[110:113], v83 offset:54272
	ds_read_b128 v[114:117], v83 offset:54304
	ds_read_b128 v[118:121], v83 offset:62976
	ds_read_b128 v[122:125], v83 offset:63008
	s_nop 3
	v_exp_f32_e32 v32, v32
	v_exp_f32_e32 v33, v33
	v_exp_f32_e32 v34, v34
	v_exp_f32_e32 v35, v35
	v_add_f32_e32 v126, v126, v32
	v_exp_f32_e32 v36, v36
	v_add_f32_e32 v126, v33, v126
	v_exp_f32_e32 v37, v37
	v_add_f32_e32 v126, v34, v126
	v_exp_f32_e32 v38, v38
	v_add_f32_e32 v126, v35, v126
	v_exp_f32_e32 v39, v39
	v_add_f32_e32 v126, v36, v126
	v_exp_f32_e32 v40, v40
	v_add_f32_e32 v126, v37, v126
	v_exp_f32_e32 v41, v41
	v_add_f32_e32 v126, v38, v126
	v_exp_f32_e32 v42, v42
	v_add_f32_e32 v126, v39, v126
	v_exp_f32_e32 v43, v43
	v_add_f32_e32 v126, v40, v126
	v_exp_f32_e32 v44, v44
	v_add_f32_e32 v126, v41, v126
	v_exp_f32_e32 v45, v45
	v_add_f32_e32 v126, v42, v126
	v_exp_f32_e32 v46, v46
	v_add_f32_e32 v126, v43, v126
	v_exp_f32_e32 v47, v47
	v_add_f32_e32 v126, v44, v126
	v_add_f32_e32 v126, v45, v126
	v_add_f32_e32 v126, v46, v126
	v_add_f32_e32 v126, v47, v126
	v_cvt_pk_bf16_f32 v130, v32, v33
	v_cvt_pk_bf16_f32 v134, v40, v41
	v_cvt_pk_bf16_f32 v131, v34, v35
	v_cvt_pk_bf16_f32 v135, v42, v43
	v_cvt_pk_bf16_f32 v132, v36, v37
	v_cvt_pk_bf16_f32 v136, v44, v45
	v_cvt_pk_bf16_f32 v133, v38, v39
	v_cvt_pk_bf16_f32 v137, v46, v47
	s_waitcnt lgkmcnt(7)
	v_mfma_f32_32x32x16_bf16 v[32:47], v[84:87], v[60:63], 0
	s_waitcnt lgkmcnt(6)
	v_mfma_f32_32x32x16_bf16 v[32:47], v[88:91], v[56:59], v[32:47]
	s_waitcnt lgkmcnt(5)
	v_mfma_f32_32x32x16_bf16 v[32:47], v[94:97], v[52:55], v[32:47]
	s_waitcnt lgkmcnt(3)
	v_mfma_f32_32x32x16_bf16 v[16:31], v[110:113], v[102:105], v[16:31]
	s_waitcnt lgkmcnt(1)
	v_mfma_f32_32x32x16_bf16 v[0:15], v[118:121], v[102:105], v[0:15]
	v_mfma_f32_32x32x16_bf16 v[32:47], v[98:101], v[48:51], v[32:47]
	v_mfma_f32_32x32x16_bf16 v[16:31], v[114:117], v[106:109], v[16:31]
	s_waitcnt lgkmcnt(0)
	v_mfma_f32_32x32x16_bf16 v[0:15], v[122:125], v[106:109], v[0:15]
	ds_read_b128 v[84:87], v93 offset:49664
	ds_read_b128 v[88:91], v93 offset:49696
	ds_read_b128 v[94:97], v93 offset:49728
	ds_read_b128 v[98:101], v93 offset:49760
	ds_read_b128 v[102:105], v83 offset:54336
	ds_read_b128 v[106:109], v83 offset:54368
	ds_read_b128 v[110:113], v83 offset:63040
	ds_read_b128 v[114:117], v83 offset:63072
	s_nop 0
	v_exp_f32_e32 v32, v32
	v_exp_f32_e32 v33, v33
	v_exp_f32_e32 v34, v34
	v_exp_f32_e32 v35, v35
	v_add_f32_e32 v93, v32, v126
	v_exp_f32_e32 v36, v36
	v_add_f32_e32 v93, v33, v93
	v_exp_f32_e32 v37, v37
	v_add_f32_e32 v93, v34, v93
	v_exp_f32_e32 v38, v38
	v_add_f32_e32 v93, v35, v93
	v_exp_f32_e32 v39, v39
	v_add_f32_e32 v93, v36, v93
	v_exp_f32_e32 v40, v40
	v_add_f32_e32 v93, v37, v93
	v_exp_f32_e32 v41, v41
	v_add_f32_e32 v93, v38, v93
	v_exp_f32_e32 v42, v42
	v_add_f32_e32 v93, v39, v93
	v_exp_f32_e32 v43, v43
	v_add_f32_e32 v93, v40, v93
	v_exp_f32_e32 v44, v44
	v_add_f32_e32 v93, v41, v93
	v_exp_f32_e32 v45, v45
	v_add_f32_e32 v93, v42, v93
	v_exp_f32_e32 v46, v46
	v_add_f32_e32 v93, v43, v93
	v_exp_f32_e32 v47, v47
	v_add_f32_e32 v93, v44, v93
	v_add_f32_e32 v93, v45, v93
	v_add_f32_e32 v93, v46, v93
	v_add_f32_e32 v93, v47, v93
	v_cvt_pk_bf16_f32 v118, v32, v33
	v_cvt_pk_bf16_f32 v122, v40, v41
	v_cvt_pk_bf16_f32 v119, v34, v35
	v_cvt_pk_bf16_f32 v123, v42, v43
	v_cvt_pk_bf16_f32 v120, v36, v37
	v_cvt_pk_bf16_f32 v124, v44, v45
	v_cvt_pk_bf16_f32 v121, v38, v39
	v_cvt_pk_bf16_f32 v125, v46, v47
	s_waitcnt lgkmcnt(3)
; #define KLOAD(kf_, base)                                                                       \
;   { _Pragma("unroll") for (int ks = 0; ks < NKS; ks++) kf_[ks] = *(const bf16x8*)((base) + kfo + ks * 32); }
; #define VLOAD(vf_, base)                                                                       \
;   { _Pragma("unroll") for (int q = 0; q < 4; q++) vf_[q] = *(const bf16x8*)((base) + vfo + (q >> 1) * 32 * VROW + (q & 1) * 32); }
; #define QKM(dst, kf_)                                                                          \
;   {                                                                                            \
;     _Pragma("unroll") for (int i = 0; i < 16; i++) dst[i] = 0.f;                               \
;     _Pragma("unroll") for (int ks = 0; ks < NKS; ks++) dst = MFMA(kf_[ks], qf[ks], dst);       \
;   }
; #define SB() __builtin_amdgcn_sched_barrier(0)
; template <int DK>
; DI void attn_core(const bf16x8 (&qf)[DK / 16], const short* Kg, const short* VTg, size_t ldvt, int ntiles, char* smem,
;                   f32x16 (&O)[2], float& lsum) {
;     ...
;   for (int t = 0; t < ntiles; t++) {
;     const int tn = t + 2 < ntiles ? t + 2 : ntiles - 1;
;     AGLOAD(tn);
;     const char* cur = smem + sc * ST;
;     const char* nxt = smem + sn * ST;
;     f32x16 Sn;
;     bf16x8 pa, pb, qa, qb;
;     bf16x8 kf[NKS], vf[4];
;     KLOAD(kf, cur + 32 * KROW);
;     SB();
;     SOFTMAX(Sc, pa, pb, l0);
;     SB();
;     QKM(Sn, kf);
;     SB();
;     KLOAD(kf, cur + 64 * KROW);
;     VLOAD(vf, cur);
;     SB();
;     SOFTMAX(Sn, qa, qb, l0);
;     SB();
;     QKM(Sc, kf);
;     PVM(vf, pa, pb);
;     SB();
;     KLOAD(kf, cur + 96 * KROW);
;     VLOAD(vf, cur + 64);
;     SB();
;     SOFTMAX(Sc, pa, pb, l0);
;     SB();
;     QKM(Sn, kf);
;     PVM(vf, qa, qb);
;     SB();
;     KLOAD(kf, nxt);
;     VLOAD(vf, cur + 128);
;     SB();
;     SOFTMAX(Sn, qa, qb, l0);
;     SB();
;     QKM(Sc, kf);
;     PVM(vf, pa, pb);
;     SB();
;     VLOAD(vf, cur + 192);
;     PVM(vf, qa, qb);
;     ASTORE(sw);
;     __syncthreads();
	v_mfma_f32_32x32x16_bf16 v[16:31], v[102:105], v[130:133], v[16:31]
	s_waitcnt lgkmcnt(1)
	v_mfma_f32_32x32x16_bf16 v[0:15], v[110:113], v[130:133], v[0:15]
	v_mfma_f32_32x32x16_bf16 v[16:31], v[106:109], v[134:137], v[16:31]
	s_waitcnt lgkmcnt(0)
	v_mfma_f32_32x32x16_bf16 v[0:15], v[114:117], v[134:137], v[0:15]
	v_mfma_f32_32x32x16_bf16 v[32:47], v[84:87], v[60:63], 0
	v_mfma_f32_32x32x16_bf16 v[32:47], v[88:91], v[56:59], v[32:47]
	v_mfma_f32_32x32x16_bf16 v[32:47], v[94:97], v[52:55], v[32:47]
	ds_read_b128 v[52:55], v83 offset:54400
	ds_read_b128 v[56:59], v83 offset:54432
	ds_read_b128 v[60:63], v83 offset:63104
	ds_read_b128 v[84:87], v83 offset:63136
	v_mfma_f32_32x32x16_bf16 v[32:47], v[98:101], v[48:51], v[32:47]
	s_nop 11
	v_exp_f32_e32 v48, v32
	v_exp_f32_e32 v49, v33
	v_exp_f32_e32 v50, v34
	v_exp_f32_e32 v51, v35
	v_exp_f32_e32 v88, v36
	v_cvt_pk_bf16_f32 v32, v48, v49
	v_add_f32_e32 v48, v93, v48
	v_exp_f32_e32 v89, v37
	v_add_f32_e32 v48, v49, v48
	v_exp_f32_e32 v90, v38
	v_add_f32_e32 v48, v50, v48
	v_exp_f32_e32 v91, v39
	v_add_f32_e32 v48, v51, v48
	v_exp_f32_e32 v40, v40
	v_exp_f32_e32 v41, v41
	v_add_f32_e32 v48, v88, v48
	v_add_f32_e32 v48, v89, v48
	v_exp_f32_e32 v42, v42
	v_add_f32_e32 v48, v90, v48
	v_exp_f32_e32 v43, v43
	v_add_f32_e32 v48, v91, v48
	v_exp_f32_e32 v44, v44
	v_cvt_pk_bf16_f32 v36, v40, v41
	v_add_f32_e32 v40, v40, v48
	v_exp_f32_e32 v45, v45
	v_add_f32_e32 v40, v41, v40
	v_exp_f32_e32 v46, v46
	v_add_f32_e32 v40, v42, v40
	v_exp_f32_e32 v47, v47
	v_add_f32_e32 v40, v43, v40
	v_add_f32_e32 v40, v44, v40
	v_add_f32_e32 v40, v45, v40
	v_add_f32_e32 v40, v46, v40
	v_cvt_pk_bf16_f32 v33, v50, v51
	v_cvt_pk_bf16_f32 v37, v42, v43
	v_cvt_pk_bf16_f32 v34, v88, v89
	v_cvt_pk_bf16_f32 v38, v44, v45
	v_cvt_pk_bf16_f32 v35, v90, v91
	v_cvt_pk_bf16_f32 v39, v46, v47
	v_add_f32_e32 v88, v47, v40
	s_waitcnt lgkmcnt(3)
	v_mfma_f32_32x32x16_bf16 v[16:31], v[52:55], v[118:121], v[16:31]
	s_waitcnt lgkmcnt(1)
	v_mfma_f32_32x32x16_bf16 v[0:15], v[60:63], v[118:121], v[0:15]
	v_mfma_f32_32x32x16_bf16 v[16:31], v[56:59], v[122:125], v[16:31]
	s_waitcnt lgkmcnt(0)
	v_mfma_f32_32x32x16_bf16 v[0:15], v[84:87], v[122:125], v[0:15]
	ds_read_b128 v[40:43], v83 offset:54464
	ds_read_b128 v[44:47], v83 offset:54496
	ds_read_b128 v[48:51], v83 offset:63168
	ds_read_b128 v[52:55], v83 offset:63200
	v_mov_b32_e32 v60, v196
	s_waitcnt vmcnt(1)
	ds_write_b128 v81, v[76:79]
	ds_write_b128 v92, v[68:71]
	ds_write_b128 v82, v[64:67] offset:18432
	s_waitcnt vmcnt(0)
	ds_write_b128 v82, v[72:75] offset:27136
	s_waitcnt lgkmcnt(0)
	s_barrier
; DI int my_tid() { int t = threadIdx.x; asm volatile("" : "+v"(t)); return t; }
; DI float bf_lo(unsigned u) { return __uint_as_float(u << 16); }
; DI float bf_hi(unsigned u) { return __uint_as_float(u & 0xffff0000u); }
; DI void attn_store(const f32x16 (&O)[2], float lsum, int tok, int col0, const short* gate, short* o, char* smem) {
;   const int tid = my_tid(), lane = tid & 63, w = tid >> 6, r = lane & 31, h = lane >> 5;
;   float l = lsum + __shfl_xor(lsum, 32);
;   float inv = __builtin_amdgcn_rcpf(l);
;   float* pw = (float*)(smem + w * (32 * 68 * 4));
;   const int tokw = tok - r;
;   const int ch = lane & 7;
;   u32x4 gpre[4];
; #pragma unroll
;   for (int j = 0; j < 4; j++) gpre[j] = *(const u32x4*)(gate + (size_t)(tokw + j * 8 + (lane >> 3)) * 1024 + col0 + ch * 8);
; #pragma unroll
;   for (int dt = 0; dt < 2; dt++)
; #pragma unroll
;     for (int q = 0; q < 4; q++) {
;       f32x4 t = {O[dt][q * 4 + 0] * inv, O[dt][q * 4 + 1] * inv, O[dt][q * 4 + 2] * inv, O[dt][q * 4 + 3] * inv};
;       *(f32x4*)(pw + r * 68 + dt * 32 + 8 * q + 4 * h) = t;
;     }
;   asm volatile("s_waitcnt lgkmcnt(0)" ::: "memory");
; #pragma unroll
;   for (int j = 0; j < 4; j++) {
;     const int row = j * 8 + (lane >> 3);
;     const size_t g = (size_t)(tokw + row) * 1024 + col0 + ch * 8;
;     const u32x4 gv = gpre[j];
;     const f32x4 a = *(const f32x4*)(pw + row * 68 + ch * 8), c = *(const f32x4*)(pw + row * 68 + ch * 8 + 4);
;     u32x4 ov;
;     ov[0] = pack_bf16(a[0] * bf_lo(gv[0]), a[1] * bf_hi(gv[0]));
;     ov[1] = pack_bf16(a[2] * bf_lo(gv[1]), a[3] * bf_hi(gv[1]));
;     ov[2] = pack_bf16(c[0] * bf_lo(gv[2]), c[1] * bf_hi(gv[2]));
;     ov[3] = pack_bf16(c[2] * bf_lo(gv[3]), c[3] * bf_hi(gv[3]));
;     __builtin_nontemporal_store(ov, (u32x4*)(o + g));
;   }
;   __syncthreads();
	v_mfma_f32_32x32x16_bf16 v[16:31], v[40:43], v[32:35], v[16:31]
	v_and_b32_e32 v61, 31, v60
	v_bfe_u32 v62, v60, 3, 3
	s_or_b32 s30, s30, 0x600
	s_movk_i32 s28, 0x2200
	s_mov_b64 s[42:43], 0
	v_mfma_f32_32x32x16_bf16 v[0:15], v[48:51], v[32:35], v[0:15]
	v_sub_u32_e32 v32, v80, v61
	v_add_u32_e32 v48, v62, v32
	v_lshlrev_b32_e32 v32, 3, v60
	v_and_b32_e32 v63, 56, v32
	v_lshlrev_b32_e32 v128, 1, v63
	v_ashrrev_i32_e32 v49, 31, v48
	v_lshl_add_u64 v[50:51], s[8:9], 0, v[128:129]
	v_lshlrev_b64 v[56:57], 11, v[48:49]
	v_lshl_add_u64 v[32:33], v[50:51], 0, v[56:57]
	v_lshl_add_u64 v[32:33], v[32:33], 0, s[30:31]
	global_load_dwordx4 v[32:35], v[32:33], off
	v_add_u32_e32 v40, 8, v48
	v_ashrrev_i32_e32 v41, 31, v40
	v_lshlrev_b64 v[58:59], 11, v[40:41]
	v_lshl_add_u64 v[40:41], v[50:51], 0, v[58:59]
	v_lshl_add_u64 v[40:41], v[40:41], 0, s[30:31]
	global_load_dwordx4 v[40:43], v[40:41], off
	v_mfma_f32_32x32x16_bf16 v[16:31], v[44:47], v[36:39], v[16:31]
	v_and_b32_e32 v45, 64, v200
	v_xor_b32_e32 v44, 32, v200
	v_add_u32_e32 v45, 64, v45
	v_cmp_lt_i32_e32 vcc, v44, v45
	s_nop 1
	v_cndmask_b32_e32 v44, v200, v44, vcc
	v_mfma_f32_32x32x16_bf16 v[0:15], v[52:55], v[36:39], v[0:15]
	v_lshrrev_b32_e32 v36, 6, v60
	v_mul_lo_u32 v55, v36, s28
	v_add_u32_e32 v36, 16, v48
	v_ashrrev_i32_e32 v37, 31, v36
	v_lshlrev_b64 v[52:53], 11, v[36:37]
	v_lshl_add_u64 v[36:37], v[50:51], 0, v[52:53]
	v_lshl_add_u64 v[36:37], v[36:37], 0, s[30:31]
	v_lshlrev_b32_e32 v44, 2, v44
	global_load_dwordx4 v[36:39], v[36:37], off
	ds_bpermute_b32 v44, v44, v88
	s_waitcnt lgkmcnt(0)
	v_add_f32_e32 v54, v88, v44
	v_add_u32_e32 v44, 24, v48
	v_ashrrev_i32_e32 v45, 31, v44
	v_lshlrev_b64 v[48:49], 11, v[44:45]
	v_lshl_add_u64 v[44:45], v[50:51], 0, v[48:49]
	v_lshl_add_u64 v[44:45], v[44:45], 0, s[30:31]
	global_load_dwordx4 v[44:47], v[44:45], off
	v_rcp_f32_e32 v50, v54
	v_lshrrev_b32_e32 v54, 1, v60
	v_mul_u32_u24_e32 v51, 0x110, v61
	v_and_b32_e32 v54, 16, v54
	v_add3_u32 v51, v55, v51, v54
	v_pk_mul_f32 v[16:17], v[16:17], v[50:51] op_sel_hi:[1,0]
	v_pk_mul_f32 v[18:19], v[18:19], v[50:51] op_sel_hi:[1,0]
	v_pk_mul_f32 v[0:1], v[0:1], v[50:51] op_sel_hi:[1,0]
	v_pk_mul_f32 v[2:3], v[2:3], v[50:51] op_sel_hi:[1,0]
	ds_write_b128 v51, v[16:19]
	v_pk_mul_f32 v[16:17], v[20:21], v[50:51] op_sel_hi:[1,0]
	v_pk_mul_f32 v[18:19], v[22:23], v[50:51] op_sel_hi:[1,0]
	ds_write_b128 v51, v[0:3] offset:128
	v_pk_mul_f32 v[0:1], v[4:5], v[50:51] op_sel_hi:[1,0]
	v_pk_mul_f32 v[2:3], v[6:7], v[50:51] op_sel_hi:[1,0]
	ds_write_b128 v51, v[16:19] offset:32
	v_pk_mul_f32 v[16:17], v[24:25], v[50:51] op_sel_hi:[1,0]
	v_pk_mul_f32 v[18:19], v[26:27], v[50:51] op_sel_hi:[1,0]
	ds_write_b128 v51, v[0:3] offset:160
	v_pk_mul_f32 v[0:1], v[8:9], v[50:51] op_sel_hi:[1,0]
	v_pk_mul_f32 v[2:3], v[10:11], v[50:51] op_sel_hi:[1,0]
	ds_write_b128 v51, v[16:19] offset:64
	v_pk_mul_f32 v[16:17], v[28:29], v[50:51] op_sel_hi:[1,0]
	v_pk_mul_f32 v[18:19], v[30:31], v[50:51] op_sel_hi:[1,0]
	ds_write_b128 v51, v[0:3] offset:192
	v_pk_mul_f32 v[0:1], v[12:13], v[50:51] op_sel_hi:[1,0]
	v_pk_mul_f32 v[2:3], v[14:15], v[50:51] op_sel_hi:[1,0]
	ds_write_b128 v51, v[16:19] offset:96
	ds_write_b128 v51, v[0:3] offset:224
	v_lshl_or_b32 v0, v63, 2, v55
	s_waitcnt lgkmcnt(0)
	v_mad_u32_u24 v12, v62, s16, v0
	ds_read_b128 v[0:3], v12
	ds_read_b128 v[4:7], v12 offset:16
	v_lshl_add_u64 v[8:9], s[14:15], 0, v[128:129]
	s_waitcnt vmcnt(3)
	v_lshlrev_b32_e32 v10, 16, v32
	v_and_b32_e32 v11, 0xffff0000, v32
	s_waitcnt lgkmcnt(1)
	v_pk_mul_f32 v[0:1], v[0:1], v[10:11]
	v_lshlrev_b32_e32 v10, 16, v33
	v_and_b32_e32 v11, 0xffff0000, v33
	v_pk_mul_f32 v[2:3], v[2:3], v[10:11]
	v_cvt_pk_bf16_f32 v0, v0, v1
	v_cvt_pk_bf16_f32 v1, v2, v3
	v_lshlrev_b32_e32 v2, 16, v34
	v_and_b32_e32 v3, 0xffff0000, v34
	s_waitcnt lgkmcnt(0)
	v_pk_mul_f32 v[2:3], v[4:5], v[2:3]
	v_lshlrev_b32_e32 v4, 16, v35
	v_and_b32_e32 v5, 0xffff0000, v35
	v_pk_mul_f32 v[4:5], v[6:7], v[4:5]
	v_cvt_pk_bf16_f32 v2, v2, v3
	v_cvt_pk_bf16_f32 v3, v4, v5
	v_lshl_add_u64 v[4:5], v[8:9], 0, v[56:57]
	v_lshl_add_u64 v[10:11], v[4:5], 0, s[30:31]
	ds_read_b128 v[4:7], v12 offset:2176
	global_store_dwordx4 v[10:11], v[0:3], off nt
	ds_read_b128 v[0:3], v12 offset:2192
	s_waitcnt vmcnt(3)
	v_lshlrev_b32_e32 v10, 16, v40
	v_and_b32_e32 v11, 0xffff0000, v40
	s_waitcnt lgkmcnt(1)
	v_pk_mul_f32 v[4:5], v[4:5], v[10:11]
	v_lshlrev_b32_e32 v10, 16, v41
	v_and_b32_e32 v11, 0xffff0000, v41
	v_pk_mul_f32 v[6:7], v[6:7], v[10:11]
	v_cvt_pk_bf16_f32 v4, v4, v5
	v_cvt_pk_bf16_f32 v5, v6, v7
	v_lshlrev_b32_e32 v6, 16, v42
	v_and_b32_e32 v7, 0xffff0000, v42
	s_waitcnt lgkmcnt(0)
	v_pk_mul_f32 v[0:1], v[0:1], v[6:7]
	s_nop 0
	v_cvt_pk_bf16_f32 v6, v0, v1
	v_lshlrev_b32_e32 v0, 16, v43
	v_and_b32_e32 v1, 0xffff0000, v43
	v_pk_mul_f32 v[0:1], v[2:3], v[0:1]
	s_nop 0
	v_cvt_pk_bf16_f32 v7, v0, v1
	v_lshl_add_u64 v[0:1], v[8:9], 0, v[58:59]
	v_lshl_add_u64 v[10:11], v[0:1], 0, s[30:31]
	ds_read_b128 v[0:3], v12 offset:4352
	global_store_dwordx4 v[10:11], v[4:7], off nt
	ds_read_b128 v[4:7], v12 offset:4368
	s_waitcnt vmcnt(3)
	v_lshlrev_b32_e32 v10, 16, v36
	v_and_b32_e32 v11, 0xffff0000, v36
	s_waitcnt lgkmcnt(1)
	v_pk_mul_f32 v[0:1], v[0:1], v[10:11]
	v_lshlrev_b32_e32 v10, 16, v37
	v_and_b32_e32 v11, 0xffff0000, v37
	v_pk_mul_f32 v[2:3], v[2:3], v[10:11]
	v_cvt_pk_bf16_f32 v0, v0, v1
	v_cvt_pk_bf16_f32 v1, v2, v3
	v_lshlrev_b32_e32 v2, 16, v38
	v_and_b32_e32 v3, 0xffff0000, v38
	s_waitcnt lgkmcnt(0)
	v_pk_mul_f32 v[2:3], v[4:5], v[2:3]
	v_lshlrev_b32_e32 v4, 16, v39
	v_and_b32_e32 v5, 0xffff0000, v39
	v_pk_mul_f32 v[4:5], v[6:7], v[4:5]
	v_cvt_pk_bf16_f32 v2, v2, v3
	v_cvt_pk_bf16_f32 v3, v4, v5
	v_lshl_add_u64 v[4:5], v[8:9], 0, v[52:53]
	v_lshl_add_u64 v[10:11], v[4:5], 0, s[30:31]
	ds_read_b128 v[4:7], v12 offset:6528
	global_store_dwordx4 v[10:11], v[0:3], off nt
	ds_read_b128 v[0:3], v12 offset:6544
	s_waitcnt vmcnt(3)
	v_lshlrev_b32_e32 v10, 16, v44
	v_and_b32_e32 v11, 0xffff0000, v44
	s_waitcnt lgkmcnt(1)
	v_pk_mul_f32 v[4:5], v[4:5], v[10:11]
	v_lshlrev_b32_e32 v10, 16, v45
	v_and_b32_e32 v11, 0xffff0000, v45
	v_pk_mul_f32 v[6:7], v[6:7], v[10:11]
	v_cvt_pk_bf16_f32 v4, v4, v5
	v_cvt_pk_bf16_f32 v5, v6, v7
	v_lshlrev_b32_e32 v6, 16, v46
	v_and_b32_e32 v7, 0xffff0000, v46
	s_waitcnt lgkmcnt(0)
	v_pk_mul_f32 v[0:1], v[0:1], v[6:7]
	s_nop 0
	v_cvt_pk_bf16_f32 v6, v0, v1
	v_lshlrev_b32_e32 v0, 16, v47
	v_and_b32_e32 v1, 0xffff0000, v47
	v_pk_mul_f32 v[0:1], v[2:3], v[0:1]
	s_nop 0
	v_cvt_pk_bf16_f32 v7, v0, v1
	v_lshl_add_u64 v[0:1], v[8:9], 0, v[48:49]
	v_lshl_add_u64 v[0:1], v[0:1], 0, s[30:31]
	global_store_dwordx4 v[0:1], v[4:7], off nt
	s_barrier

; DI int my_tid() { int t = threadIdx.x; asm volatile("" : "+v"(t)); return t; }
; template <int DK>
; DI void attn_core(const bf16x8 (&qf)[DK / 16], const short* Kg, const short* VTg, size_t ldvt, int ntiles, char* smem,
;                   f32x16 (&O)[2], float& lsum) {
;     ...
;   const int kfo = pr * KROW + h * 16;
;   const int vfo = KT_BYTES + r * VROW + h * 16;
;   AGLOAD(0);
;   ASTORE(0);
;   AGLOAD(ntiles > 1 ? 1 : 0);
;   ASTORE(1);
;   __syncthreads();
; DI void memattn_item(PRef p, int layer, int mt, int head, char* smem) {
;   const int tid = my_tid(), lane = tid & 63, w = tid >> 6, r = lane & 31, h = lane >> 5;
;   const int tok = mt * 256 + w * 32 + r;
;   const int seq = tok_seq(mt * 256);
;   const short* Q = (const short*)(p.ws + OFF_QMEM);
;   bf16x8 qf[4];
; #pragma unroll
;   for (int ks = 0; ks < 4; ks++) qf[ks] = *(const bf16x8*)(Q + (size_t)tok * 256 + head * 64 + ks * 16 + 8 * h);
;   const size_t hb = ((size_t)(layer * NSEQ + seq) * 4 + head) * 256 * 64;
;   f32x16 O[2];
;   float lsum;
;   attn_core<64>(qf, (const short*)(p.ws + OFF_KMEM) + hb, (const short*)(p.ws + OFF_VMEM) + hb, 256, 2, smem, O, lsum);
.LBB0_175:
	v_mov_b32_e32 v2, v196
	s_ashr_i32 s14, s16, 2
	s_lshl_b32 s15, s14, 8
	v_ashrrev_i32_e32 v0, 1, v2
	v_and_b32_e32 v0, 0xffffffe0, v0
	v_add_u32_e32 v0, s15, v0
	v_and_or_b32 v80, v2, 31, v0
	v_ashrrev_i32_e32 v81, 31, v80
	s_and_b32 s20, s16, 3
	v_lshlrev_b64 v[0:1], 9, v[80:81]
	v_lshl_add_u64 v[0:1], s[4:5], 0, v[0:1]
	s_lshl_b32 s30, s20, 7
	v_lshrrev_b32_e32 v2, 1, v2
	v_lshl_add_u64 v[0:1], v[0:1], 0, s[30:31]
	s_waitcnt vmcnt(7)
	v_and_b32_e32 v128, 16, v2
	v_lshl_add_u64 v[0:1], v[0:1], 0, v[128:129]
	s_addk_i32 s15, 0xc000
	v_mov_b32_e32 v2, v196
	global_load_dwordx4 v[60:63], v[0:1], off
	global_load_dwordx4 v[56:59], v[0:1], off offset:32
	global_load_dwordx4 v[52:55], v[0:1], off offset:64
	global_load_dwordx4 v[48:51], v[0:1], off offset:96
	s_lshr_b32 s15, s15, 12
	s_add_i32 s15, s15, 1
	v_lshlrev_b32_e32 v0, 1, v2
	v_and_b32_e32 v10, 8, v0
	v_ashrrev_i32_e32 v0, 31, v2
	s_cmp_gt_i32 s14, 63
	v_lshrrev_b32_e32 v0, 29, v0
	s_cselect_b32 s14, s15, 0
	s_mul_i32 s15, s28, 17
	v_add_u32_e32 v0, v2, v0
	s_add_i32 s14, s14, s15
	s_mov_b32 s15, s31
	v_lshrrev_b32_e32 v0, 3, v0
	s_lshl_b64 s[18:19], s[14:15], 17
	s_lshl_b32 s14, s20, 15
	v_add_lshl_u32 v81, v0, v2, 4
	v_add_u32_e32 v0, 0x200, v2
	s_or_b32 s18, s18, s14
	v_ashrrev_i32_e32 v1, 31, v0
	v_lshlrev_b32_e32 v4, 4, v2
	s_add_u32 s14, s10, s18
	v_lshrrev_b32_e32 v1, 29, v1
	v_and_b32_e32 v128, 0xf0, v4
	v_lshlrev_b32_e32 v4, 3, v2
	s_addc_u32 s15, s11, s19
	v_add_u32_e32 v1, v0, v1
	v_ashrrev_i32_e32 v16, 4, v2
	v_ashrrev_i32_e32 v5, 31, v4
	s_add_u32 s18, s12, s18
	v_lshrrev_b32_e32 v1, 3, v1
	v_ashrrev_i32_e32 v17, 31, v16
	v_lshlrev_b64 v[18:19], 1, v[4:5]
	v_add_u32_e32 v4, 0x1000, v4
	s_addc_u32 s19, s13, s19
	v_add_lshl_u32 v92, v1, v0, 4
	v_lshlrev_b64 v[0:1], 9, v[16:17]
	v_ashrrev_i32_e32 v5, 31, v4
	v_lshrrev_b32_e32 v3, 1, v2
	v_lshl_add_u64 v[8:9], s[18:19], 0, v[0:1]
	v_lshl_add_u64 v[0:1], s[14:15], 0, v[18:19]
	v_lshlrev_b64 v[20:21], 1, v[4:5]
	v_and_b32_e32 v32, 31, v2
	v_and_b32_e32 v11, 4, v3
	v_and_b32_e32 v12, 19, v2
	v_and_b32_e32 v33, 16, v3
	global_load_dwordx4 v[0:3], v[0:1], off
	v_lshl_add_u64 v[4:5], s[14:15], 0, v[20:21]
	v_lshl_add_u64 v[84:85], v[8:9], 0, v[128:129]
	global_load_dwordx4 v[4:7], v[4:5], off
	v_or3_b32 v10, v12, v10, v11
	v_add_co_u32_e32 v86, vcc, s84, v84
	v_mad_u32_u24 v93, v10, s21, v33
	global_load_dwordx4 v[8:11], v[84:85], off
	v_addc_co_u32_e32 v87, vcc, 0, v85, vcc
	global_load_dwordx4 v[12:15], v[86:87], off
	s_add_u32 s14, s14, 0x4000
	s_addc_u32 s15, s15, 0
	v_mad_u64_u32 v[82:83], s[18:19], v16, s36, v[128:129]
	v_lshl_add_u64 v[88:89], s[14:15], 0, v[18:19]
	v_lshl_add_u64 v[90:91], s[14:15], 0, v[20:21]
	v_add_u32_e32 v94, 0x11800, v82
	global_load_dwordx4 v[64:67], v[88:89], off
	global_load_dwordx4 v[68:71], v[90:91], off
	global_load_dwordx4 v[72:75], v[84:85], off offset:256
	global_load_dwordx4 v[76:79], v[86:87], off offset:256
	s_waitcnt vmcnt(7)
	ds_write_b128 v81, v[0:3]
	s_waitcnt vmcnt(6)
	ds_write_b128 v92, v[4:7]
	s_waitcnt vmcnt(5)
	ds_write_b128 v82, v[8:11] offset:18432
	s_waitcnt vmcnt(4)
	ds_write_b128 v82, v[12:15] offset:27136
	s_waitcnt vmcnt(3)
	ds_write_b128 v81, v[64:67] offset:35840
	s_waitcnt vmcnt(2)
	ds_write_b128 v92, v[68:71] offset:35840
	s_waitcnt vmcnt(1)
	ds_write_b128 v82, v[72:75] offset:54272
	s_waitcnt vmcnt(0)
	ds_write_b128 v82, v[76:79] offset:62976
	s_waitcnt lgkmcnt(0)
	s_barrier
	ds_read_b128 v[0:3], v93
	ds_read_b128 v[16:19], v93 offset:32
	ds_read_b128 v[20:23], v93 offset:64
	ds_read_b128 v[24:27], v93 offset:96
	global_load_dwordx4 v[64:67], v[88:89], off
	global_load_dwordx4 v[72:75], v[90:91], off
	global_load_dwordx4 v[68:71], v[84:85], off offset:256
	global_load_dwordx4 v[76:79], v[86:87], off offset:256
	s_waitcnt lgkmcnt(3)
	v_mfma_f32_32x32x16_bf16 v[0:15], v[0:3], v[60:63], 0
	s_waitcnt lgkmcnt(2)
	v_mfma_f32_32x32x16_bf16 v[0:15], v[16:19], v[56:59], v[0:15]
	s_waitcnt lgkmcnt(1)
	v_mfma_f32_32x32x16_bf16 v[0:15], v[20:23], v[52:55], v[0:15]
	s_waitcnt lgkmcnt(0)
	v_mfma_f32_32x32x16_bf16 v[0:15], v[24:27], v[48:51], v[0:15]
	ds_read_b128 v[16:19], v93 offset:4608
	ds_read_b128 v[20:23], v93 offset:4640
	ds_read_b128 v[24:27], v93 offset:4672
	ds_read_b128 v[28:31], v93 offset:4704
	s_nop 7
	v_exp_f32_e32 v0, v0
	v_exp_f32_e32 v1, v1
	v_exp_f32_e32 v2, v2
	v_exp_f32_e32 v3, v3
	v_add_f32_e32 v34, 0, v0
	v_exp_f32_e32 v4, v4
	v_add_f32_e32 v34, v1, v34
	v_exp_f32_e32 v5, v5
	v_add_f32_e32 v34, v2, v34
	v_exp_f32_e32 v6, v6
	v_add_f32_e32 v34, v3, v34
	v_exp_f32_e32 v7, v7
	v_add_f32_e32 v34, v4, v34
	v_exp_f32_e32 v8, v8
	v_add_f32_e32 v34, v5, v34
	v_exp_f32_e32 v9, v9
	v_add_f32_e32 v34, v6, v34
	v_exp_f32_e32 v10, v10
	v_add_f32_e32 v34, v7, v34
	v_exp_f32_e32 v11, v11
	v_add_f32_e32 v34, v8, v34
	v_exp_f32_e32 v12, v12
	v_add_f32_e32 v34, v9, v34
	v_exp_f32_e32 v13, v13
	v_add_f32_e32 v34, v10, v34
	v_exp_f32_e32 v14, v14
	v_add_f32_e32 v34, v11, v34
	v_exp_f32_e32 v15, v15
	v_add_f32_e32 v34, v12, v34
	v_add_f32_e32 v34, v13, v34
	v_add_f32_e32 v34, v14, v34
	v_add_f32_e32 v34, v15, v34
	v_cvt_pk_bf16_f32 v96, v0, v1
	v_cvt_pk_bf16_f32 v100, v8, v9
	v_cvt_pk_bf16_f32 v97, v2, v3
	v_cvt_pk_bf16_f32 v101, v10, v11
	v_cvt_pk_bf16_f32 v98, v4, v5
	v_cvt_pk_bf16_f32 v102, v12, v13
	v_cvt_pk_bf16_f32 v99, v6, v7
	v_cvt_pk_bf16_f32 v103, v14, v15
	s_waitcnt lgkmcnt(3)
	v_mfma_f32_32x32x16_bf16 v[0:15], v[16:19], v[60:63], 0
	s_waitcnt lgkmcnt(2)
	v_mfma_f32_32x32x16_bf16 v[0:15], v[20:23], v[56:59], v[0:15]
	s_waitcnt lgkmcnt(1)
	v_mfma_f32_32x32x16_bf16 v[0:15], v[24:27], v[52:55], v[0:15]
	s_waitcnt lgkmcnt(0)
; #define KLOAD(kf_, base)                                                                       \
;   { _Pragma("unroll") for (int ks = 0; ks < NKS; ks++) kf_[ks] = *(const bf16x8*)((base) + kfo + ks * 32); }
; #define VLOAD(vf_, base)                                                                       \
;   { _Pragma("unroll") for (int q = 0; q < 4; q++) vf_[q] = *(const bf16x8*)((base) + vfo + (q >> 1) * 32 * VROW + (q & 1) * 32); }
; #define QKM(dst, kf_)                                                                          \
;   {                                                                                            \
;     _Pragma("unroll") for (int i = 0; i < 16; i++) dst[i] = 0.f;                               \
;     _Pragma("unroll") for (int ks = 0; ks < NKS; ks++) dst = MFMA(kf_[ks], qf[ks], dst);       \
;   }
; #define SB() __builtin_amdgcn_sched_barrier(0)
; template <int DK>
; DI void attn_core(const bf16x8 (&qf)[DK / 16], const short* Kg, const short* VTg, size_t ldvt, int ntiles, char* smem,
;                   f32x16 (&O)[2], float& lsum) {
;     ...
;   for (int t = 0; t < ntiles; t++) {
;     const int tn = t + 2 < ntiles ? t + 2 : ntiles - 1;
;     AGLOAD(tn);
;     const char* cur = smem + sc * ST;
;     const char* nxt = smem + sn * ST;
;     f32x16 Sn;
;     bf16x8 pa, pb, qa, qb;
;     bf16x8 kf[NKS], vf[4];
;     KLOAD(kf, cur + 32 * KROW);
;     SB();
;     SOFTMAX(Sc, pa, pb, l0);
;     SB();
;     QKM(Sn, kf);
;     SB();
;     KLOAD(kf, cur + 64 * KROW);
;     VLOAD(vf, cur);
;     SB();
;     SOFTMAX(Sn, qa, qb, l0);
;     SB();
;     QKM(Sc, kf);
;     PVM(vf, pa, pb);
;     SB();
;     KLOAD(kf, cur + 96 * KROW);
;     VLOAD(vf, cur + 64);
;     SB();
;     SOFTMAX(Sc, pa, pb, l0);
;     SB();
;     QKM(Sn, kf);
;     PVM(vf, qa, qb);
;     SB();
;     KLOAD(kf, nxt);
;     VLOAD(vf, cur + 128);
;     SB();
;     SOFTMAX(Sn, qa, qb, l0);
;     SB();
;     QKM(Sc, kf);
;     PVM(vf, pa, pb);
;     SB();
;     VLOAD(vf, cur + 192);
;     PVM(vf, qa, qb);
;     ASTORE(sw);
;     __syncthreads();
	v_mfma_f32_32x32x16_bf16 v[0:15], v[28:31], v[48:51], v[0:15]
	v_mad_u32_u24 v83, v32, s36, v33
	ds_read_b128 v[16:19], v93 offset:9216
	ds_read_b128 v[20:23], v93 offset:9248
	ds_read_b128 v[24:27], v93 offset:9280
	ds_read_b128 v[28:31], v93 offset:9312
	ds_read_b128 v[104:107], v83 offset:18432
	ds_read_b128 v[108:111], v83 offset:18464
	ds_read_b128 v[112:115], v83 offset:27136
	ds_read_b128 v[116:119], v83 offset:27168
	s_nop 2
	v_exp_f32_e32 v0, v0
	v_exp_f32_e32 v1, v1
	v_exp_f32_e32 v2, v2
	v_exp_f32_e32 v3, v3
	v_add_f32_e32 v32, v0, v34
	v_exp_f32_e32 v4, v4
	v_add_f32_e32 v32, v1, v32
	v_exp_f32_e32 v5, v5
	v_add_f32_e32 v32, v2, v32
	v_exp_f32_e32 v6, v6
	v_add_f32_e32 v32, v3, v32
	v_exp_f32_e32 v7, v7
	v_add_f32_e32 v32, v4, v32
	v_exp_f32_e32 v8, v8
	v_add_f32_e32 v32, v5, v32
	v_exp_f32_e32 v9, v9
	v_add_f32_e32 v32, v6, v32
	v_exp_f32_e32 v10, v10
	v_add_f32_e32 v32, v7, v32
	v_exp_f32_e32 v11, v11
	v_add_f32_e32 v32, v8, v32
	v_exp_f32_e32 v12, v12
	v_add_f32_e32 v32, v9, v32
	v_exp_f32_e32 v13, v13
	v_add_f32_e32 v32, v10, v32
	v_exp_f32_e32 v14, v14
	v_add_f32_e32 v32, v11, v32
	v_exp_f32_e32 v15, v15
	v_add_f32_e32 v32, v12, v32
	v_add_f32_e32 v32, v13, v32
	v_add_f32_e32 v32, v14, v32
	v_add_f32_e32 v95, v15, v32
	v_cvt_pk_bf16_f32 v120, v0, v1
	v_cvt_pk_bf16_f32 v124, v8, v9
	v_cvt_pk_bf16_f32 v121, v2, v3
	v_cvt_pk_bf16_f32 v125, v10, v11
	v_cvt_pk_bf16_f32 v122, v4, v5
	v_cvt_pk_bf16_f32 v126, v12, v13
	v_cvt_pk_bf16_f32 v123, v6, v7
	v_cvt_pk_bf16_f32 v127, v14, v15
	s_waitcnt lgkmcnt(7)
	v_mfma_f32_32x32x16_bf16 v[32:47], v[16:19], v[60:63], 0
	s_waitcnt lgkmcnt(6)
	v_mfma_f32_32x32x16_bf16 v[32:47], v[20:23], v[56:59], v[32:47]
	s_waitcnt lgkmcnt(5)
	v_mfma_f32_32x32x16_bf16 v[32:47], v[24:27], v[52:55], v[32:47]
	s_waitcnt lgkmcnt(4)
	v_mfma_f32_32x32x16_bf16 v[32:47], v[28:31], v[48:51], v[32:47]
	s_waitcnt lgkmcnt(3)
	v_mfma_f32_32x32x16_bf16 v[16:31], v[104:107], v[96:99], 0
	s_waitcnt lgkmcnt(1)
	v_mfma_f32_32x32x16_bf16 v[0:15], v[112:115], v[96:99], 0
	v_mfma_f32_32x32x16_bf16 v[16:31], v[108:111], v[100:103], v[16:31]
	s_waitcnt lgkmcnt(0)
	v_mfma_f32_32x32x16_bf16 v[0:15], v[116:119], v[100:103], v[0:15]
	ds_read_b128 v[96:99], v93 offset:13824
	ds_read_b128 v[100:103], v93 offset:13856
	ds_read_b128 v[104:107], v93 offset:13888
	ds_read_b128 v[108:111], v93 offset:13920
	ds_read_b128 v[112:115], v83 offset:18496
	ds_read_b128 v[116:119], v83 offset:18528
	ds_read_b128 v[130:133], v83 offset:27200
	ds_read_b128 v[134:137], v83 offset:27232
	v_exp_f32_e32 v32, v32
	v_exp_f32_e32 v33, v33
	v_exp_f32_e32 v34, v34
	v_exp_f32_e32 v35, v35
	v_add_f32_e32 v95, v32, v95
	v_exp_f32_e32 v36, v36
	v_add_f32_e32 v95, v33, v95
	v_exp_f32_e32 v37, v37
	v_add_f32_e32 v95, v34, v95
	v_exp_f32_e32 v38, v38
	v_add_f32_e32 v95, v35, v95
	v_exp_f32_e32 v39, v39
	v_add_f32_e32 v95, v36, v95
	v_exp_f32_e32 v40, v40
	v_add_f32_e32 v95, v37, v95
	v_exp_f32_e32 v41, v41
	v_add_f32_e32 v95, v38, v95
	v_exp_f32_e32 v42, v42
	v_add_f32_e32 v95, v39, v95
	v_exp_f32_e32 v43, v43
	v_add_f32_e32 v95, v40, v95
	v_exp_f32_e32 v44, v44
	v_add_f32_e32 v95, v41, v95
	v_exp_f32_e32 v45, v45
	v_add_f32_e32 v95, v42, v95
	v_exp_f32_e32 v46, v46
	v_add_f32_e32 v95, v43, v95
	v_exp_f32_e32 v47, v47
	v_add_f32_e32 v95, v44, v95
	v_add_f32_e32 v95, v45, v95
	v_add_f32_e32 v95, v46, v95
	v_add_f32_e32 v95, v47, v95
	v_cvt_pk_bf16_f32 v138, v32, v33
	v_cvt_pk_bf16_f32 v142, v40, v41
	v_cvt_pk_bf16_f32 v139, v34, v35
	v_cvt_pk_bf16_f32 v143, v42, v43
	v_cvt_pk_bf16_f32 v140, v36, v37
	v_cvt_pk_bf16_f32 v144, v44, v45
	v_cvt_pk_bf16_f32 v141, v38, v39
	v_cvt_pk_bf16_f32 v145, v46, v47
	s_waitcnt lgkmcnt(3)
	v_mfma_f32_32x32x16_bf16 v[16:31], v[112:115], v[120:123], v[16:31]
	s_waitcnt lgkmcnt(1)
	v_mfma_f32_32x32x16_bf16 v[0:15], v[130:133], v[120:123], v[0:15]
	v_mfma_f32_32x32x16_bf16 v[16:31], v[116:119], v[124:127], v[16:31]
	s_waitcnt lgkmcnt(0)
	v_mfma_f32_32x32x16_bf16 v[0:15], v[134:137], v[124:127], v[0:15]
	v_mfma_f32_32x32x16_bf16 v[32:47], v[96:99], v[60:63], 0
	v_mfma_f32_32x32x16_bf16 v[32:47], v[100:103], v[56:59], v[32:47]
	v_mfma_f32_32x32x16_bf16 v[32:47], v[104:107], v[52:55], v[32:47]
	ds_read_b128 v[96:99], v93 offset:35840
	ds_read_b128 v[100:103], v93 offset:35872
	ds_read_b128 v[104:107], v93 offset:35904
	ds_read_b128 v[112:115], v93 offset:35936
	ds_read_b128 v[116:119], v83 offset:18560
	ds_read_b128 v[120:123], v83 offset:18592
	ds_read_b128 v[124:127], v83 offset:27264
	ds_read_b128 v[130:133], v83 offset:27296
	v_mfma_f32_32x32x16_bf16 v[32:47], v[108:111], v[48:51], v[32:47]
	s_nop 11
	v_exp_f32_e32 v108, v32
	v_exp_f32_e32 v109, v33
	v_exp_f32_e32 v110, v34
	v_exp_f32_e32 v111, v35
	v_exp_f32_e32 v128, v36
	v_add_f32_e32 v95, v95, v108
	v_exp_f32_e32 v134, v37
	v_add_f32_e32 v95, v109, v95
	v_exp_f32_e32 v135, v38
	v_add_f32_e32 v95, v110, v95
	v_exp_f32_e32 v136, v39
	v_add_f32_e32 v95, v111, v95
	v_exp_f32_e32 v40, v40
	v_exp_f32_e32 v41, v41
	v_add_f32_e32 v95, v128, v95
	v_add_f32_e32 v95, v134, v95
	v_exp_f32_e32 v42, v42
	v_add_f32_e32 v95, v135, v95
	v_exp_f32_e32 v43, v43
	v_add_f32_e32 v95, v136, v95
	v_exp_f32_e32 v44, v44
	v_cvt_pk_bf16_f32 v36, v40, v41
	v_add_f32_e32 v40, v40, v95
	v_exp_f32_e32 v45, v45
	v_add_f32_e32 v40, v41, v40
	v_exp_f32_e32 v46, v46
	v_add_f32_e32 v40, v42, v40
	v_exp_f32_e32 v47, v47
	v_add_f32_e32 v40, v43, v40
	v_add_f32_e32 v40, v44, v40
	v_add_f32_e32 v40, v45, v40
	v_add_f32_e32 v40, v46, v40
	v_cvt_pk_bf16_f32 v32, v108, v109
	v_cvt_pk_bf16_f32 v33, v110, v111
	v_cvt_pk_bf16_f32 v37, v42, v43
	v_cvt_pk_bf16_f32 v34, v128, v134
	v_cvt_pk_bf16_f32 v38, v44, v45
	v_cvt_pk_bf16_f32 v35, v135, v136
	v_cvt_pk_bf16_f32 v39, v46, v47
	v_add_f32_e32 v108, v47, v40
	s_waitcnt lgkmcnt(3)
	v_mfma_f32_32x32x16_bf16 v[16:31], v[116:119], v[138:141], v[16:31]
	s_waitcnt lgkmcnt(1)
	v_mfma_f32_32x32x16_bf16 v[0:15], v[124:127], v[138:141], v[0:15]
	v_mfma_f32_32x32x16_bf16 v[16:31], v[120:123], v[142:145], v[16:31]
	s_waitcnt lgkmcnt(0)
	v_mfma_f32_32x32x16_bf16 v[0:15], v[130:133], v[142:145], v[0:15]
	ds_read_b128 v[40:43], v83 offset:18624
	v_add_u32_e32 v95, 0x11800, v81
	s_waitcnt lgkmcnt(0)
	v_mfma_f32_32x32x16_bf16 v[16:31], v[40:43], v[32:35], v[16:31]
	ds_read_b128 v[40:43], v83 offset:27328
	s_waitcnt lgkmcnt(0)
	v_mfma_f32_32x32x16_bf16 v[0:15], v[40:43], v[32:35], v[0:15]
	ds_read_b128 v[32:35], v83 offset:18656
	s_waitcnt lgkmcnt(0)
	v_mfma_f32_32x32x16_bf16 v[16:31], v[32:35], v[36:39], v[16:31]
	ds_read_b128 v[32:35], v83 offset:27360
	s_waitcnt vmcnt(3)
	ds_write_b128 v95, v[64:67]
	v_add_u32_e32 v64, 0x11800, v92
	s_waitcnt vmcnt(2)
	ds_write_b128 v64, v[72:75]
	s_waitcnt vmcnt(1)
	ds_write_b128 v94, v[68:71] offset:18432
	s_waitcnt vmcnt(0)
	ds_write_b128 v94, v[76:79] offset:27136
	s_waitcnt lgkmcnt(0)
	s_barrier
; #define KLOAD(kf_, base)                                                                       \
;   { _Pragma("unroll") for (int ks = 0; ks < NKS; ks++) kf_[ks] = *(const bf16x8*)((base) + kfo + ks * 32); }
; #define VLOAD(vf_, base)                                                                       \
;   { _Pragma("unroll") for (int q = 0; q < 4; q++) vf_[q] = *(const bf16x8*)((base) + vfo + (q >> 1) * 32 * VROW + (q & 1) * 32); }
; #define QKM(dst, kf_)                                                                          \
;   {                                                                                            \
;     _Pragma("unroll") for (int i = 0; i < 16; i++) dst[i] = 0.f;                               \
;     _Pragma("unroll") for (int ks = 0; ks < NKS; ks++) dst = MFMA(kf_[ks], qf[ks], dst);       \
;   }
; #define SB() __builtin_amdgcn_sched_barrier(0)
; template <int DK>
; DI void attn_core(const bf16x8 (&qf)[DK / 16], const short* Kg, const short* VTg, size_t ldvt, int ntiles, char* smem,
;                   f32x16 (&O)[2], float& lsum) {
;     ...
;   for (int t = 0; t < ntiles; t++) {
;     const int tn = t + 2 < ntiles ? t + 2 : ntiles - 1;
;     AGLOAD(tn);
;     const char* cur = smem + sc * ST;
;     const char* nxt = smem + sn * ST;
;     f32x16 Sn;
;     bf16x8 pa, pb, qa, qb;
;     bf16x8 kf[NKS], vf[4];
;     KLOAD(kf, cur + 32 * KROW);
;     SB();
;     SOFTMAX(Sc, pa, pb, l0);
;     SB();
;     QKM(Sn, kf);
;     SB();
;     KLOAD(kf, cur + 64 * KROW);
;     VLOAD(vf, cur);
;     SB();
;     SOFTMAX(Sn, qa, qb, l0);
;     SB();
;     QKM(Sc, kf);
;     PVM(vf, pa, pb);
;     SB();
;     KLOAD(kf, cur + 96 * KROW);
;     VLOAD(vf, cur + 64);
;     SB();
;     SOFTMAX(Sc, pa, pb, l0);
;     SB();
;     QKM(Sn, kf);
;     PVM(vf, qa, qb);
;     SB();
;     KLOAD(kf, nxt);
;     VLOAD(vf, cur + 128);
;     SB();
;     SOFTMAX(Sn, qa, qb, l0);
;     SB();
;     QKM(Sc, kf);
;     PVM(vf, pa, pb);
;     SB();
;     VLOAD(vf, cur + 192);
;     PVM(vf, qa, qb);
	global_load_dwordx4 v[68:71], v[90:91], off
	global_load_dwordx4 v[64:67], v[84:85], off offset:256
	global_load_dwordx4 v[76:79], v[88:89], off
	global_load_dwordx4 v[72:75], v[86:87], off offset:256
	v_mfma_f32_32x32x16_bf16 v[0:15], v[32:35], v[36:39], v[0:15]
	v_mfma_f32_32x32x16_bf16 v[32:47], v[96:99], v[60:63], 0
	v_mfma_f32_32x32x16_bf16 v[32:47], v[100:103], v[56:59], v[32:47]
	ds_read_b128 v[84:87], v93 offset:40448
	ds_read_b128 v[88:91], v93 offset:40480
	ds_read_b128 v[94:97], v93 offset:40512
	ds_read_b128 v[98:101], v93 offset:40544
	v_mfma_f32_32x32x16_bf16 v[32:47], v[104:107], v[52:55], v[32:47]
	v_mfma_f32_32x32x16_bf16 v[32:47], v[112:115], v[48:51], v[32:47]
	s_nop 11
	v_exp_f32_e32 v32, v32
	v_exp_f32_e32 v33, v33
	v_exp_f32_e32 v34, v34
	v_exp_f32_e32 v35, v35
	v_add_f32_e32 v102, v108, v32
	v_exp_f32_e32 v36, v36
	v_add_f32_e32 v102, v33, v102
	v_exp_f32_e32 v37, v37
	v_add_f32_e32 v102, v34, v102
	v_exp_f32_e32 v38, v38
	v_add_f32_e32 v102, v35, v102
	v_exp_f32_e32 v39, v39
	v_add_f32_e32 v102, v36, v102
	v_exp_f32_e32 v40, v40
	v_add_f32_e32 v102, v37, v102
	v_exp_f32_e32 v41, v41
	v_add_f32_e32 v102, v38, v102
	v_exp_f32_e32 v42, v42
	v_add_f32_e32 v102, v39, v102
	v_exp_f32_e32 v43, v43
	v_add_f32_e32 v102, v40, v102
	v_exp_f32_e32 v44, v44
	v_add_f32_e32 v102, v41, v102
	v_exp_f32_e32 v45, v45
	v_add_f32_e32 v102, v42, v102
	v_exp_f32_e32 v46, v46
	v_add_f32_e32 v102, v43, v102
	v_exp_f32_e32 v47, v47
	v_add_f32_e32 v102, v44, v102
	v_add_f32_e32 v102, v45, v102
	v_add_f32_e32 v102, v46, v102
	v_add_f32_e32 v126, v47, v102
	v_cvt_pk_bf16_f32 v102, v32, v33
	v_cvt_pk_bf16_f32 v106, v40, v41
	v_cvt_pk_bf16_f32 v103, v34, v35
	v_cvt_pk_bf16_f32 v107, v42, v43
	v_cvt_pk_bf16_f32 v104, v36, v37
	v_cvt_pk_bf16_f32 v108, v44, v45
	v_cvt_pk_bf16_f32 v105, v38, v39
	v_cvt_pk_bf16_f32 v109, v46, v47
	s_waitcnt lgkmcnt(3)
	v_mfma_f32_32x32x16_bf16 v[32:47], v[84:87], v[60:63], 0
	s_waitcnt lgkmcnt(2)
	v_mfma_f32_32x32x16_bf16 v[32:47], v[88:91], v[56:59], v[32:47]
	s_waitcnt lgkmcnt(1)
	v_mfma_f32_32x32x16_bf16 v[32:47], v[94:97], v[52:55], v[32:47]
	s_waitcnt lgkmcnt(0)
	v_mfma_f32_32x32x16_bf16 v[32:47], v[98:101], v[48:51], v[32:47]
	ds_read_b128 v[84:87], v93 offset:45056
	ds_read_b128 v[88:91], v93 offset:45088
	ds_read_b128 v[94:97], v93 offset:45120
	ds_read_b128 v[98:101], v93 offset:45152
	ds_read_b128 v[110:113], v83 offset:54272
	ds_read_b128 v[114:117], v83 offset:54304
	ds_read_b128 v[118:121], v83 offset:62976
	ds_read_b128 v[122:125], v83 offset:63008
	s_nop 3
	v_exp_f32_e32 v32, v32
	v_exp_f32_e32 v33, v33
	v_exp_f32_e32 v34, v34
	v_exp_f32_e32 v35, v35
	v_add_f32_e32 v126, v126, v32
	v_exp_f32_e32 v36, v36
	v_add_f32_e32 v126, v33, v126
	v_exp_f32_e32 v37, v37
	v_add_f32_e32 v126, v34, v126
	v_exp_f32_e32 v38, v38
	v_add_f32_e32 v126, v35, v126
	v_exp_f32_e32 v39, v39
	v_add_f32_e32 v126, v36, v126
	v_exp_f32_e32 v40, v40
	v_add_f32_e32 v126, v37, v126
	v_exp_f32_e32 v41, v41
	v_add_f32_e32 v126, v38, v126
	v_exp_f32_e32 v42, v42
	v_add_f32_e32 v126, v39, v126
	v_exp_f32_e32 v43, v43
	v_add_f32_e32 v126, v40, v126
	v_exp_f32_e32 v44, v44
	v_add_f32_e32 v126, v41, v126
	v_exp_f32_e32 v45, v45
	v_add_f32_e32 v126, v42, v126
	v_exp_f32_e32 v46, v46
	v_add_f32_e32 v126, v43, v126
	v_exp_f32_e32 v47, v47
	v_add_f32_e32 v126, v44, v126
	v_add_f32_e32 v126, v45, v126
	v_add_f32_e32 v126, v46, v126
	v_add_f32_e32 v126, v47, v126
	v_cvt_pk_bf16_f32 v130, v32, v33
	v_cvt_pk_bf16_f32 v134, v40, v41
	v_cvt_pk_bf16_f32 v131, v34, v35
	v_cvt_pk_bf16_f32 v135, v42, v43
	v_cvt_pk_bf16_f32 v132, v36, v37
	v_cvt_pk_bf16_f32 v136, v44, v45
	v_cvt_pk_bf16_f32 v133, v38, v39
	v_cvt_pk_bf16_f32 v137, v46, v47
	s_waitcnt lgkmcnt(7)
	v_mfma_f32_32x32x16_bf16 v[32:47], v[84:87], v[60:63], 0
	s_waitcnt lgkmcnt(6)
	v_mfma_f32_32x32x16_bf16 v[32:47], v[88:91], v[56:59], v[32:47]
	s_waitcnt lgkmcnt(5)
	v_mfma_f32_32x32x16_bf16 v[32:47], v[94:97], v[52:55], v[32:47]
	s_waitcnt lgkmcnt(3)
	v_mfma_f32_32x32x16_bf16 v[16:31], v[110:113], v[102:105], v[16:31]
	s_waitcnt lgkmcnt(1)
	v_mfma_f32_32x32x16_bf16 v[0:15], v[118:121], v[102:105], v[0:15]
	v_mfma_f32_32x32x16_bf16 v[32:47], v[98:101], v[48:51], v[32:47]
	v_mfma_f32_32x32x16_bf16 v[16:31], v[114:117], v[106:109], v[16:31]
	s_waitcnt lgkmcnt(0)
	v_mfma_f32_32x32x16_bf16 v[0:15], v[122:125], v[106:109], v[0:15]
	ds_read_b128 v[84:87], v93 offset:49664
	ds_read_b128 v[88:91], v93 offset:49696
	ds_read_b128 v[94:97], v93 offset:49728
	ds_read_b128 v[98:101], v93 offset:49760
	ds_read_b128 v[102:105], v83 offset:54336
	ds_read_b128 v[106:109], v83 offset:54368
	ds_read_b128 v[110:113], v83 offset:63040
	ds_read_b128 v[114:117], v83 offset:63072
	s_nop 0
	v_exp_f32_e32 v32, v32
	v_exp_f32_e32 v33, v33
	v_exp_f32_e32 v34, v34
	v_exp_f32_e32 v35, v35
	v_add_f32_e32 v93, v32, v126
	v_exp_f32_e32 v36, v36
	v_add_f32_e32 v93, v33, v93
	v_exp_f32_e32 v37, v37
	v_add_f32_e32 v93, v34, v93
	v_exp_f32_e32 v38, v38
	v_add_f32_e32 v93, v35, v93
	v_exp_f32_e32 v39, v39
	v_add_f32_e32 v93, v36, v93
	v_exp_f32_e32 v40, v40
	v_add_f32_e32 v93, v37, v93
	v_exp_f32_e32 v41, v41
	v_add_f32_e32 v93, v38, v93
	v_exp_f32_e32 v42, v42
	v_add_f32_e32 v93, v39, v93
	v_exp_f32_e32 v43, v43
	v_add_f32_e32 v93, v40, v93
	v_exp_f32_e32 v44, v44
	v_add_f32_e32 v93, v41, v93
	v_exp_f32_e32 v45, v45
	v_add_f32_e32 v93, v42, v93
	v_exp_f32_e32 v46, v46
	v_add_f32_e32 v93, v43, v93
	v_exp_f32_e32 v47, v47
	v_add_f32_e32 v93, v44, v93
	v_add_f32_e32 v93, v45, v93
	v_add_f32_e32 v93, v46, v93
	v_add_f32_e32 v93, v47, v93
	v_cvt_pk_bf16_f32 v118, v32, v33
	v_cvt_pk_bf16_f32 v122, v40, v41
	v_cvt_pk_bf16_f32 v119, v34, v35
	v_cvt_pk_bf16_f32 v123, v42, v43
	v_cvt_pk_bf16_f32 v120, v36, v37
	v_cvt_pk_bf16_f32 v124, v44, v45
	v_cvt_pk_bf16_f32 v121, v38, v39
	v_cvt_pk_bf16_f32 v125, v46, v47
	s_waitcnt lgkmcnt(3)
; #define VLOAD(vf_, base)                                                                       \
;   { _Pragma("unroll") for (int q = 0; q < 4; q++) vf_[q] = *(const bf16x8*)((base) + vfo + (q >> 1) * 32 * VROW + (q & 1) * 32); }
; #define QKM(dst, kf_)                                                                          \
;   {                                                                                            \
;     _Pragma("unroll") for (int i = 0; i < 16; i++) dst[i] = 0.f;                               \
;     _Pragma("unroll") for (int ks = 0; ks < NKS; ks++) dst = MFMA(kf_[ks], qf[ks], dst);       \
;   }
; #define SB() __builtin_amdgcn_sched_barrier(0)
; template <int DK>
; DI void attn_core(const bf16x8 (&qf)[DK / 16], const short* Kg, const short* VTg, size_t ldvt, int ntiles, char* smem,
;                   f32x16 (&O)[2], float& lsum) {
;     ...
;     SOFTMAX(Sn, qa, qb, l0);
;     SB();
;     QKM(Sc, kf);
;     PVM(vf, pa, pb);
;     SB();
;     VLOAD(vf, cur + 192);
;     PVM(vf, qa, qb);
;     ASTORE(sw);
;     __syncthreads();
	v_mfma_f32_32x32x16_bf16 v[16:31], v[102:105], v[130:133], v[16:31]
	s_waitcnt lgkmcnt(1)
	v_mfma_f32_32x32x16_bf16 v[0:15], v[110:113], v[130:133], v[0:15]
	v_mfma_f32_32x32x16_bf16 v[16:31], v[106:109], v[134:137], v[16:31]
	s_waitcnt lgkmcnt(0)
	v_mfma_f32_32x32x16_bf16 v[0:15], v[114:117], v[134:137], v[0:15]
	v_mfma_f32_32x32x16_bf16 v[32:47], v[84:87], v[60:63], 0
	v_mfma_f32_32x32x16_bf16 v[32:47], v[88:91], v[56:59], v[32:47]
	v_mfma_f32_32x32x16_bf16 v[32:47], v[94:97], v[52:55], v[32:47]
	ds_read_b128 v[52:55], v83 offset:54400
	ds_read_b128 v[56:59], v83 offset:54432
	ds_read_b128 v[60:63], v83 offset:63104
	ds_read_b128 v[84:87], v83 offset:63136
	v_mfma_f32_32x32x16_bf16 v[32:47], v[98:101], v[48:51], v[32:47]
	s_nop 11
	v_exp_f32_e32 v48, v32
	v_exp_f32_e32 v49, v33
	v_exp_f32_e32 v50, v34
	v_exp_f32_e32 v51, v35
	v_exp_f32_e32 v88, v36
	v_cvt_pk_bf16_f32 v32, v48, v49
	v_add_f32_e32 v48, v93, v48
	v_exp_f32_e32 v89, v37
	v_add_f32_e32 v48, v49, v48
	v_exp_f32_e32 v90, v38
	v_add_f32_e32 v48, v50, v48
	v_exp_f32_e32 v91, v39
	v_add_f32_e32 v48, v51, v48
	v_exp_f32_e32 v40, v40
	v_exp_f32_e32 v41, v41
	v_add_f32_e32 v48, v88, v48
	v_add_f32_e32 v48, v89, v48
	v_exp_f32_e32 v42, v42
	v_add_f32_e32 v48, v90, v48
	v_exp_f32_e32 v43, v43
	v_add_f32_e32 v48, v91, v48
	v_exp_f32_e32 v44, v44
	v_cvt_pk_bf16_f32 v36, v40, v41
	v_add_f32_e32 v40, v40, v48
	v_exp_f32_e32 v45, v45
	v_add_f32_e32 v40, v41, v40
	v_exp_f32_e32 v46, v46
	v_add_f32_e32 v40, v42, v40
	v_exp_f32_e32 v47, v47
	v_add_f32_e32 v40, v43, v40
	v_add_f32_e32 v40, v44, v40
	v_add_f32_e32 v40, v45, v40
	v_add_f32_e32 v40, v46, v40
	v_cvt_pk_bf16_f32 v33, v50, v51
	v_cvt_pk_bf16_f32 v37, v42, v43
	v_cvt_pk_bf16_f32 v34, v88, v89
	v_cvt_pk_bf16_f32 v38, v44, v45
	v_cvt_pk_bf16_f32 v35, v90, v91
	v_cvt_pk_bf16_f32 v39, v46, v47
	v_add_f32_e32 v88, v47, v40
	s_waitcnt lgkmcnt(3)
	v_mfma_f32_32x32x16_bf16 v[16:31], v[52:55], v[118:121], v[16:31]
	s_waitcnt lgkmcnt(1)
	v_mfma_f32_32x32x16_bf16 v[0:15], v[60:63], v[118:121], v[0:15]
	v_mfma_f32_32x32x16_bf16 v[16:31], v[56:59], v[122:125], v[16:31]
	s_waitcnt lgkmcnt(0)
	v_mfma_f32_32x32x16_bf16 v[0:15], v[84:87], v[122:125], v[0:15]
	ds_read_b128 v[40:43], v83 offset:54464
	ds_read_b128 v[44:47], v83 offset:54496
	ds_read_b128 v[48:51], v83 offset:63168
	ds_read_b128 v[52:55], v83 offset:63200
	v_mov_b32_e32 v60, v196
	s_waitcnt vmcnt(1)
	ds_write_b128 v81, v[76:79]
	ds_write_b128 v92, v[68:71]
	ds_write_b128 v82, v[64:67] offset:18432
	s_waitcnt vmcnt(0)
	ds_write_b128 v82, v[72:75] offset:27136
	s_waitcnt lgkmcnt(0)
	s_barrier
; DI int my_tid() { int t = threadIdx.x; asm volatile("" : "+v"(t)); return t; }
; DI float bf_lo(unsigned u) { return __uint_as_float(u << 16); }
; DI float bf_hi(unsigned u) { return __uint_as_float(u & 0xffff0000u); }
; DI void attn_store(const f32x16 (&O)[2], float lsum, int tok, int col0, const short* gate, short* o, char* smem) {
;   const int tid = my_tid(), lane = tid & 63, w = tid >> 6, r = lane & 31, h = lane >> 5;
;   float l = lsum + __shfl_xor(lsum, 32);
;   float inv = __builtin_amdgcn_rcpf(l);
;   float* pw = (float*)(smem + w * (32 * 68 * 4));
;   const int tokw = tok - r;
;   const int ch = lane & 7;
;   u32x4 gpre[4];
; #pragma unroll
;   for (int j = 0; j < 4; j++) gpre[j] = *(const u32x4*)(gate + (size_t)(tokw + j * 8 + (lane >> 3)) * 1024 + col0 + ch * 8);
; #pragma unroll
;   for (int dt = 0; dt < 2; dt++)
; #pragma unroll
;     for (int q = 0; q < 4; q++) {
;       f32x4 t = {O[dt][q * 4 + 0] * inv, O[dt][q * 4 + 1] * inv, O[dt][q * 4 + 2] * inv, O[dt][q * 4 + 3] * inv};
;       *(f32x4*)(pw + r * 68 + dt * 32 + 8 * q + 4 * h) = t;
;     }
;   asm volatile("s_waitcnt lgkmcnt(0)" ::: "memory");
; #pragma unroll
;   for (int j = 0; j < 4; j++) {
;     const int row = j * 8 + (lane >> 3);
;     const size_t g = (size_t)(tokw + row) * 1024 + col0 + ch * 8;
;     const u32x4 gv = gpre[j];
;     const f32x4 a = *(const f32x4*)(pw + row * 68 + ch * 8), c = *(const f32x4*)(pw + row * 68 + ch * 8 + 4);
;     u32x4 ov;
;     ov[0] = pack_bf16(a[0] * bf_lo(gv[0]), a[1] * bf_hi(gv[0]));
;     ov[1] = pack_bf16(a[2] * bf_lo(gv[1]), a[3] * bf_hi(gv[1]));
;     ov[2] = pack_bf16(c[0] * bf_lo(gv[2]), c[1] * bf_hi(gv[2]));
;     ov[3] = pack_bf16(c[2] * bf_lo(gv[3]), c[3] * bf_hi(gv[3]));
;     __builtin_nontemporal_store(ov, (u32x4*)(o + g));
;   }
;   __syncthreads();
; }
	v_mfma_f32_32x32x16_bf16 v[16:31], v[40:43], v[32:35], v[16:31]
	v_and_b32_e32 v61, 31, v60
	v_bfe_u32 v62, v60, 3, 3
	s_or_b32 s30, s30, 0x600
	s_add_i32 s16, s16, s51
	s_cmpk_gt_i32 s16, 0x4ff
	v_mfma_f32_32x32x16_bf16 v[0:15], v[48:51], v[32:35], v[0:15]
	v_sub_u32_e32 v32, v80, v61
	v_add_u32_e32 v48, v62, v32
	v_lshlrev_b32_e32 v32, 3, v60
	v_and_b32_e32 v63, 56, v32
	v_lshlrev_b32_e32 v128, 1, v63
	v_ashrrev_i32_e32 v49, 31, v48
	v_lshl_add_u64 v[50:51], s[6:7], 0, v[128:129]
	v_lshlrev_b64 v[56:57], 11, v[48:49]
	v_lshl_add_u64 v[32:33], v[50:51], 0, v[56:57]
	v_lshl_add_u64 v[32:33], v[32:33], 0, s[30:31]
	global_load_dwordx4 v[32:35], v[32:33], off
	v_add_u32_e32 v40, 8, v48
	v_ashrrev_i32_e32 v41, 31, v40
	v_lshlrev_b64 v[58:59], 11, v[40:41]
	v_lshl_add_u64 v[40:41], v[50:51], 0, v[58:59]
	v_lshl_add_u64 v[40:41], v[40:41], 0, s[30:31]
	global_load_dwordx4 v[40:43], v[40:41], off
	v_mfma_f32_32x32x16_bf16 v[16:31], v[44:47], v[36:39], v[16:31]
	v_and_b32_e32 v45, 64, v200
	v_xor_b32_e32 v44, 32, v200
	v_add_u32_e32 v45, 64, v45
	v_cmp_lt_i32_e32 vcc, v44, v45
	s_nop 1
	v_cndmask_b32_e32 v44, v200, v44, vcc
	v_mfma_f32_32x32x16_bf16 v[0:15], v[52:55], v[36:39], v[0:15]
	v_lshrrev_b32_e32 v36, 6, v60
	v_mul_lo_u32 v55, v36, s22
	v_add_u32_e32 v36, 16, v48
	v_ashrrev_i32_e32 v37, 31, v36
	v_lshlrev_b64 v[52:53], 11, v[36:37]
	v_lshl_add_u64 v[36:37], v[50:51], 0, v[52:53]
	v_lshl_add_u64 v[36:37], v[36:37], 0, s[30:31]
	v_lshlrev_b32_e32 v44, 2, v44
	global_load_dwordx4 v[36:39], v[36:37], off
	ds_bpermute_b32 v44, v44, v88
	s_waitcnt lgkmcnt(0)
	v_add_f32_e32 v54, v88, v44
	v_add_u32_e32 v44, 24, v48
	v_ashrrev_i32_e32 v45, 31, v44
	v_lshlrev_b64 v[48:49], 11, v[44:45]
	v_lshl_add_u64 v[44:45], v[50:51], 0, v[48:49]
	v_lshl_add_u64 v[44:45], v[44:45], 0, s[30:31]
	global_load_dwordx4 v[44:47], v[44:45], off
	v_rcp_f32_e32 v50, v54
	v_lshrrev_b32_e32 v54, 1, v60
	v_mul_u32_u24_e32 v51, 0x110, v61
	v_and_b32_e32 v54, 16, v54
	v_add3_u32 v51, v55, v51, v54
	v_pk_mul_f32 v[16:17], v[16:17], v[50:51] op_sel_hi:[1,0]
	v_pk_mul_f32 v[18:19], v[18:19], v[50:51] op_sel_hi:[1,0]
	v_pk_mul_f32 v[0:1], v[0:1], v[50:51] op_sel_hi:[1,0]
	v_pk_mul_f32 v[2:3], v[2:3], v[50:51] op_sel_hi:[1,0]
	ds_write_b128 v51, v[16:19]
	v_pk_mul_f32 v[16:17], v[20:21], v[50:51] op_sel_hi:[1,0]
	v_pk_mul_f32 v[18:19], v[22:23], v[50:51] op_sel_hi:[1,0]
	ds_write_b128 v51, v[0:3] offset:128
	v_pk_mul_f32 v[0:1], v[4:5], v[50:51] op_sel_hi:[1,0]
	v_pk_mul_f32 v[2:3], v[6:7], v[50:51] op_sel_hi:[1,0]
	ds_write_b128 v51, v[16:19] offset:32
	v_pk_mul_f32 v[16:17], v[24:25], v[50:51] op_sel_hi:[1,0]
	v_pk_mul_f32 v[18:19], v[26:27], v[50:51] op_sel_hi:[1,0]
	ds_write_b128 v51, v[0:3] offset:160
	v_pk_mul_f32 v[0:1], v[8:9], v[50:51] op_sel_hi:[1,0]
	v_pk_mul_f32 v[2:3], v[10:11], v[50:51] op_sel_hi:[1,0]
	ds_write_b128 v51, v[16:19] offset:64
	v_pk_mul_f32 v[16:17], v[28:29], v[50:51] op_sel_hi:[1,0]
	v_pk_mul_f32 v[18:19], v[30:31], v[50:51] op_sel_hi:[1,0]
	ds_write_b128 v51, v[0:3] offset:192
	v_pk_mul_f32 v[0:1], v[12:13], v[50:51] op_sel_hi:[1,0]
	v_pk_mul_f32 v[2:3], v[14:15], v[50:51] op_sel_hi:[1,0]
	ds_write_b128 v51, v[16:19] offset:96
	ds_write_b128 v51, v[0:3] offset:224
	v_lshl_or_b32 v0, v63, 2, v55
	s_waitcnt lgkmcnt(0)
	v_mad_u32_u24 v12, v62, s36, v0
	ds_read_b128 v[0:3], v12
	ds_read_b128 v[4:7], v12 offset:16
	v_lshl_add_u64 v[8:9], s[8:9], 0, v[128:129]
	s_waitcnt vmcnt(3)
	v_lshlrev_b32_e32 v10, 16, v32
	v_and_b32_e32 v11, 0xffff0000, v32
	s_waitcnt lgkmcnt(1)
	v_pk_mul_f32 v[0:1], v[0:1], v[10:11]
	v_lshlrev_b32_e32 v10, 16, v33
	v_and_b32_e32 v11, 0xffff0000, v33
	v_pk_mul_f32 v[2:3], v[2:3], v[10:11]
	v_cvt_pk_bf16_f32 v0, v0, v1
	v_cvt_pk_bf16_f32 v1, v2, v3
	v_lshlrev_b32_e32 v2, 16, v34
	v_and_b32_e32 v3, 0xffff0000, v34
	s_waitcnt lgkmcnt(0)
	v_pk_mul_f32 v[2:3], v[4:5], v[2:3]
	v_lshlrev_b32_e32 v4, 16, v35
	v_and_b32_e32 v5, 0xffff0000, v35
	v_pk_mul_f32 v[4:5], v[6:7], v[4:5]
	v_cvt_pk_bf16_f32 v2, v2, v3
	v_cvt_pk_bf16_f32 v3, v4, v5
	v_lshl_add_u64 v[4:5], v[8:9], 0, v[56:57]
	v_lshl_add_u64 v[10:11], v[4:5], 0, s[30:31]
	ds_read_b128 v[4:7], v12 offset:2176
	global_store_dwordx4 v[10:11], v[0:3], off nt
	ds_read_b128 v[0:3], v12 offset:2192
	s_waitcnt vmcnt(3)
	v_lshlrev_b32_e32 v10, 16, v40
	v_and_b32_e32 v11, 0xffff0000, v40
	s_waitcnt lgkmcnt(1)
	v_pk_mul_f32 v[4:5], v[4:5], v[10:11]
	v_lshlrev_b32_e32 v10, 16, v41
	v_and_b32_e32 v11, 0xffff0000, v41
	v_pk_mul_f32 v[6:7], v[6:7], v[10:11]
	v_cvt_pk_bf16_f32 v4, v4, v5
	v_cvt_pk_bf16_f32 v5, v6, v7
	v_lshlrev_b32_e32 v6, 16, v42
	v_and_b32_e32 v7, 0xffff0000, v42
	s_waitcnt lgkmcnt(0)
	v_pk_mul_f32 v[0:1], v[0:1], v[6:7]
	s_nop 0
	v_cvt_pk_bf16_f32 v6, v0, v1
	v_lshlrev_b32_e32 v0, 16, v43
	v_and_b32_e32 v1, 0xffff0000, v43
	v_pk_mul_f32 v[0:1], v[2:3], v[0:1]
	s_nop 0
	v_cvt_pk_bf16_f32 v7, v0, v1
	v_lshl_add_u64 v[0:1], v[8:9], 0, v[58:59]
	v_lshl_add_u64 v[10:11], v[0:1], 0, s[30:31]
	ds_read_b128 v[0:3], v12 offset:4352
	global_store_dwordx4 v[10:11], v[4:7], off nt
	ds_read_b128 v[4:7], v12 offset:4368
	s_waitcnt vmcnt(3)
	v_lshlrev_b32_e32 v10, 16, v36
	v_and_b32_e32 v11, 0xffff0000, v36
	s_waitcnt lgkmcnt(1)
	v_pk_mul_f32 v[0:1], v[0:1], v[10:11]
	v_lshlrev_b32_e32 v10, 16, v37
	v_and_b32_e32 v11, 0xffff0000, v37
	v_pk_mul_f32 v[2:3], v[2:3], v[10:11]
	v_cvt_pk_bf16_f32 v0, v0, v1
	v_cvt_pk_bf16_f32 v1, v2, v3
	v_lshlrev_b32_e32 v2, 16, v38
	v_and_b32_e32 v3, 0xffff0000, v38
	s_waitcnt lgkmcnt(0)
	v_pk_mul_f32 v[2:3], v[4:5], v[2:3]
	v_lshlrev_b32_e32 v4, 16, v39
	v_and_b32_e32 v5, 0xffff0000, v39
	v_pk_mul_f32 v[4:5], v[6:7], v[4:5]
	v_cvt_pk_bf16_f32 v2, v2, v3
	v_cvt_pk_bf16_f32 v3, v4, v5
	v_lshl_add_u64 v[4:5], v[8:9], 0, v[52:53]
	v_lshl_add_u64 v[10:11], v[4:5], 0, s[30:31]
	ds_read_b128 v[4:7], v12 offset:6528
	global_store_dwordx4 v[10:11], v[0:3], off nt
	ds_read_b128 v[0:3], v12 offset:6544
	s_waitcnt vmcnt(3)
	v_lshlrev_b32_e32 v10, 16, v44
	v_and_b32_e32 v11, 0xffff0000, v44
	s_waitcnt lgkmcnt(1)
	v_pk_mul_f32 v[4:5], v[4:5], v[10:11]
	v_lshlrev_b32_e32 v10, 16, v45
	v_and_b32_e32 v11, 0xffff0000, v45
	v_pk_mul_f32 v[6:7], v[6:7], v[10:11]
	v_cvt_pk_bf16_f32 v4, v4, v5
	v_cvt_pk_bf16_f32 v5, v6, v7
	v_lshlrev_b32_e32 v6, 16, v46
	v_and_b32_e32 v7, 0xffff0000, v46
	s_waitcnt lgkmcnt(0)
	v_pk_mul_f32 v[0:1], v[0:1], v[6:7]
	s_nop 0
	v_cvt_pk_bf16_f32 v6, v0, v1
	v_lshlrev_b32_e32 v0, 16, v47
	v_and_b32_e32 v1, 0xffff0000, v47
	v_pk_mul_f32 v[0:1], v[2:3], v[0:1]
	s_nop 0
	v_cvt_pk_bf16_f32 v7, v0, v1
	v_lshl_add_u64 v[0:1], v[8:9], 0, v[48:49]
	v_lshl_add_u64 v[0:1], v[0:1], 0, s[30:31]
	global_store_dwordx4 v[0:1], v[4:7], off nt
	s_barrier
	s_cbranch_scc0 .LBB0_175
